# K-loop loader VALU eliminated: LDS read bases pre-biased with immediate offsets, K wrap compare moved to SALU
# baseline (speedup 1.0000x reference)
.LBB0_306:
	s_add_u32 s46, s50, 0x100
	s_addc_u32 s47, s51, 0
	s_add_u32 s3, s50, 0xfffff900
	s_addc_u32 s33, s51, -1
	s_cmp_gt_u32 s46, 0x7ff
	s_cselect_b32 s46, s3, s46
	s_cselect_b32 s47, s33, s47
	s_add_u32 s3, s28, s46
	s_addc_u32 s33, s29, s47
	s_add_u32 s69, s24, s46
	s_addc_u32 s94, s25, s47
	s_add_i32 vcc_lo, 0, 0x10000
	v_add_u32_e32 v75, vcc_lo, v73
	ds_read_b128 v[76:79], v75
	ds_read_b128 v[80:83], v75 offset:1024
	ds_read_b128 v[84:87], v75 offset:2048
	ds_read_b128 v[88:91], v75 offset:3072
	s_cmp_eq_u32 s1, 12
	s_cselect_b32 s97, s35, s33
	s_cselect_b32 s96, s34, s3
	s_cselect_b32 s95, s90, s94
	s_cselect_b32 s94, s15, s69
	s_add_u32 s3, s28, s50
	s_addc_u32 s33, s29, s51
	s_add_u32 s50, s3, 0x48080
	s_addc_u32 s51, s33, 0
	v_lshl_add_u64 v[124:125], s[50:51], 0, v[68:69]
	s_add_i32 m0, s23, 0xc000
	ds_read_b128 v[92:95], v74
	ds_read_b128 v[96:99], v74 offset:1024
	ds_read_b128 v[100:103], v74 offset:2048
	ds_read_b128 v[104:107], v74 offset:3072
	ds_read_b128 v[108:111], v74 offset:4096
	ds_read_b128 v[112:115], v74 offset:5120
	ds_read_b128 v[116:119], v74 offset:6144
	ds_read_b128 v[120:123], v74 offset:7168
	global_load_lds_dwordx4 v[124:125], off
	v_lshl_add_u64 v[124:125], s[50:51], 0, v[66:67]
	s_add_i32 m0, s23, 0xe000
	s_nop 0
	global_load_lds_dwordx4 v[124:125], off
	s_waitcnt vmcnt(8)
	s_waitcnt lgkmcnt(0)
	s_barrier
	s_setprio 1
	s_waitcnt lgkmcnt(0)
	v_mfma_f32_16x16x32_bf16 v[60:63], v[76:79], v[92:95], v[60:63]
	v_mfma_f32_16x16x32_bf16 v[56:59], v[84:87], v[92:95], v[56:59]
	v_mfma_f32_16x16x32_bf16 v[52:55], v[76:79], v[100:103], v[52:55]
	v_mfma_f32_16x16x32_bf16 v[48:51], v[84:87], v[100:103], v[48:51]
	v_mfma_f32_16x16x32_bf16 v[44:47], v[76:79], v[108:111], v[44:47]
	v_mfma_f32_16x16x32_bf16 v[40:43], v[84:87], v[108:111], v[40:43]
	v_mfma_f32_16x16x32_bf16 v[36:39], v[76:79], v[116:119], v[36:39]
	v_mfma_f32_16x16x32_bf16 v[32:35], v[84:87], v[116:119], v[32:35]
	v_mfma_f32_16x16x32_bf16 v[60:63], v[80:83], v[96:99], v[60:63]
	v_mfma_f32_16x16x32_bf16 v[56:59], v[88:91], v[96:99], v[56:59]
	v_mfma_f32_16x16x32_bf16 v[52:55], v[80:83], v[104:107], v[52:55]
	v_mfma_f32_16x16x32_bf16 v[48:51], v[88:91], v[104:107], v[48:51]
	v_mfma_f32_16x16x32_bf16 v[44:47], v[80:83], v[112:115], v[44:47]
	v_mfma_f32_16x16x32_bf16 v[40:43], v[88:91], v[112:115], v[40:43]
	v_mfma_f32_16x16x32_bf16 v[36:39], v[80:83], v[120:123], v[36:39]
	v_mfma_f32_16x16x32_bf16 v[32:35], v[88:91], v[120:123], v[32:35]
	s_setprio 0
	s_setprio 1
	s_setprio 0
	s_barrier
	s_add_i32 s3, vcc_lo, s60
	v_lshl_add_u64 v[124:125], s[94:95], 0, v[188:189]
	s_mov_b32 m0, s3
	ds_read_b128 v[92:95], v74 offset:16384
	ds_read_b128 v[96:99], v74 offset:17408
	ds_read_b128 v[100:103], v74 offset:18432
	ds_read_b128 v[104:107], v74 offset:19456
	ds_read_b128 v[108:111], v74 offset:20480
	ds_read_b128 v[112:115], v74 offset:21504
	ds_read_b128 v[116:119], v74 offset:22528
	ds_read_b128 v[120:123], v74 offset:23552
	global_load_lds_dwordx4 v[124:125], off
	s_add_i32 m0, s3, 0x2000
	s_add_u32 s50, s94, 0x40000
	v_lshl_add_u64 v[126:127], s[94:95], 0, v[64:65]
	s_addc_u32 s51, s95, 0
	global_load_lds_dwordx4 v[126:127], off
	v_lshl_add_u64 v[128:129], s[50:51], 0, v[188:189]
	s_mov_b32 m0, s76
	v_lshl_add_u64 v[130:131], s[96:97], 0, v[66:67]
	global_load_lds_dwordx4 v[128:129], off
	v_lshl_add_u64 v[128:129], s[50:51], 0, v[64:65]
	s_mov_b32 m0, s77
	s_nop 0
	global_load_lds_dwordx4 v[128:129], off
	v_lshl_add_u64 v[128:129], s[96:97], 0, v[68:69]
	s_mov_b32 m0, s23
	s_nop 0
	global_load_lds_dwordx4 v[128:129], off
	s_mov_b32 m0, s87
	s_nop 0
	global_load_lds_dwordx4 v[130:131], off
	s_waitcnt vmcnt(8)
	s_waitcnt lgkmcnt(0)
	s_barrier
	s_setprio 1
	s_waitcnt lgkmcnt(0)
	v_mfma_f32_16x16x32_bf16 v[28:31], v[76:79], v[92:95], v[28:31]
	v_mfma_f32_16x16x32_bf16 v[24:27], v[84:87], v[92:95], v[24:27]
	v_mfma_f32_16x16x32_bf16 v[20:23], v[76:79], v[100:103], v[20:23]
	v_mfma_f32_16x16x32_bf16 v[16:19], v[84:87], v[100:103], v[16:19]
	v_mfma_f32_16x16x32_bf16 v[12:15], v[76:79], v[108:111], v[12:15]
	v_mfma_f32_16x16x32_bf16 v[8:11], v[84:87], v[108:111], v[8:11]
	v_mfma_f32_16x16x32_bf16 v[4:7], v[76:79], v[116:119], v[4:7]
	v_mfma_f32_16x16x32_bf16 v[0:3], v[84:87], v[116:119], v[0:3]
	v_mfma_f32_16x16x32_bf16 v[28:31], v[80:83], v[96:99], v[28:31]
	v_mfma_f32_16x16x32_bf16 v[24:27], v[88:91], v[96:99], v[24:27]
	v_mfma_f32_16x16x32_bf16 v[20:23], v[80:83], v[104:107], v[20:23]
	v_mfma_f32_16x16x32_bf16 v[16:19], v[88:91], v[104:107], v[16:19]
	v_mfma_f32_16x16x32_bf16 v[12:15], v[80:83], v[112:115], v[12:15]
	v_mfma_f32_16x16x32_bf16 v[8:11], v[88:91], v[112:115], v[8:11]
	v_mfma_f32_16x16x32_bf16 v[4:7], v[80:83], v[120:123], v[4:7]
	v_mfma_f32_16x16x32_bf16 v[0:3], v[88:91], v[120:123], v[0:3]
	s_setprio 0
	s_setprio 1
	s_setprio 0
	s_barrier
	s_add_i32 s3, 0, 0x18000
	v_add_u32_e32 v75, s3, v73
	ds_read_b128 v[76:79], v75
	ds_read_b128 v[80:83], v75 offset:1024
	ds_read_b128 v[84:87], v75 offset:2048
	ds_read_b128 v[88:91], v75 offset:3072
	s_add_u32 s50, s96, 0x48000
	s_addc_u32 s51, s97, 0
	s_mov_b32 m0, s89
	v_lshl_add_u64 v[132:133], s[50:51], 0, v[68:69]
	ds_read_b128 v[92:95], v74 offset:32768
	ds_read_b128 v[96:99], v74 offset:33792
	ds_read_b128 v[100:103], v74 offset:34816
	ds_read_b128 v[104:107], v74 offset:35840
	ds_read_b128 v[108:111], v74 offset:36864
	ds_read_b128 v[112:115], v74 offset:37888
	ds_read_b128 v[116:119], v74 offset:38912
	ds_read_b128 v[120:123], v74 offset:39936
	global_load_lds_dwordx4 v[132:133], off
	v_lshl_add_u64 v[132:133], s[50:51], 0, v[66:67]
	s_mov_b32 m0, s91
	s_nop 0
	global_load_lds_dwordx4 v[132:133], off
	s_waitcnt vmcnt(8)
	s_waitcnt lgkmcnt(0)
	s_barrier
	s_setprio 1
	s_waitcnt lgkmcnt(0)
	v_mfma_f32_16x16x32_bf16 v[60:63], v[76:79], v[92:95], v[60:63]
	v_mfma_f32_16x16x32_bf16 v[56:59], v[84:87], v[92:95], v[56:59]
	v_mfma_f32_16x16x32_bf16 v[52:55], v[76:79], v[100:103], v[52:55]
	v_mfma_f32_16x16x32_bf16 v[48:51], v[84:87], v[100:103], v[48:51]
	v_mfma_f32_16x16x32_bf16 v[44:47], v[76:79], v[108:111], v[44:47]
	v_mfma_f32_16x16x32_bf16 v[40:43], v[84:87], v[108:111], v[40:43]
	v_mfma_f32_16x16x32_bf16 v[36:39], v[76:79], v[116:119], v[36:39]
	v_mfma_f32_16x16x32_bf16 v[32:35], v[84:87], v[116:119], v[32:35]
	v_mfma_f32_16x16x32_bf16 v[60:63], v[80:83], v[96:99], v[60:63]
	v_mfma_f32_16x16x32_bf16 v[56:59], v[88:91], v[96:99], v[56:59]
	v_mfma_f32_16x16x32_bf16 v[52:55], v[80:83], v[104:107], v[52:55]
	v_mfma_f32_16x16x32_bf16 v[48:51], v[88:91], v[104:107], v[48:51]
	v_mfma_f32_16x16x32_bf16 v[44:47], v[80:83], v[112:115], v[44:47]
	v_mfma_f32_16x16x32_bf16 v[40:43], v[88:91], v[112:115], v[40:43]
	v_mfma_f32_16x16x32_bf16 v[36:39], v[80:83], v[120:123], v[36:39]
	v_mfma_f32_16x16x32_bf16 v[32:35], v[88:91], v[120:123], v[32:35]
	s_setprio 0
	s_setprio 1
	s_setprio 0
	s_barrier
	s_add_i32 s3, s3, s60
	v_lshl_add_u64 v[124:125], v[124:125], 0, s[72:73]
	s_mov_b32 m0, s3
	ds_read_b128 v[92:95], v74 offset:49152
	ds_read_b128 v[96:99], v74 offset:50176
	ds_read_b128 v[100:103], v74 offset:51200
	ds_read_b128 v[104:107], v74 offset:52224
	ds_read_b128 v[108:111], v74 offset:53248
	ds_read_b128 v[112:115], v74 offset:54272
	ds_read_b128 v[116:119], v74 offset:55296
	ds_read_b128 v[120:123], v74 offset:56320
	global_load_lds_dwordx4 v[124:125], off
	s_add_i32 m0, s3, 0x2000
	s_add_u32 s50, s94, 0x40080
	v_lshl_add_u64 v[124:125], v[126:127], 0, s[72:73]
	s_addc_u32 s51, s95, 0
	global_load_lds_dwordx4 v[124:125], off
	v_lshl_add_u64 v[124:125], s[50:51], 0, v[188:189]
	s_mov_b32 m0, s99
	s_nop 0
	global_load_lds_dwordx4 v[124:125], off
	v_lshl_add_u64 v[124:125], s[50:51], 0, v[64:65]
	s_mov_b32 m0, s26
	s_nop 0
	global_load_lds_dwordx4 v[124:125], off
	v_lshl_add_u64 v[124:125], v[128:129], 0, s[72:73]
	s_mov_b32 m0, s93
	s_nop 0
	global_load_lds_dwordx4 v[124:125], off
	v_lshl_add_u64 v[124:125], v[130:131], 0, s[72:73]
	s_mov_b32 m0, s98
	s_nop 0
	global_load_lds_dwordx4 v[124:125], off
	s_waitcnt vmcnt(8)
	s_waitcnt lgkmcnt(0)
	s_barrier
	s_setprio 1
	s_waitcnt lgkmcnt(0)
	v_mfma_f32_16x16x32_bf16 v[28:31], v[76:79], v[92:95], v[28:31]
	v_mfma_f32_16x16x32_bf16 v[24:27], v[84:87], v[92:95], v[24:27]
	v_mfma_f32_16x16x32_bf16 v[20:23], v[76:79], v[100:103], v[20:23]
	v_mfma_f32_16x16x32_bf16 v[16:19], v[84:87], v[100:103], v[16:19]
	v_mfma_f32_16x16x32_bf16 v[12:15], v[76:79], v[108:111], v[12:15]
	v_mfma_f32_16x16x32_bf16 v[8:11], v[84:87], v[108:111], v[8:11]
	v_mfma_f32_16x16x32_bf16 v[4:7], v[76:79], v[116:119], v[4:7]
	v_mfma_f32_16x16x32_bf16 v[0:3], v[84:87], v[116:119], v[0:3]
	v_mfma_f32_16x16x32_bf16 v[28:31], v[80:83], v[96:99], v[28:31]
	v_mfma_f32_16x16x32_bf16 v[24:27], v[88:91], v[96:99], v[24:27]
	v_mfma_f32_16x16x32_bf16 v[20:23], v[80:83], v[104:107], v[20:23]
	v_mfma_f32_16x16x32_bf16 v[16:19], v[88:91], v[104:107], v[16:19]
	v_mfma_f32_16x16x32_bf16 v[12:15], v[80:83], v[112:115], v[12:15]
	v_mfma_f32_16x16x32_bf16 v[8:11], v[88:91], v[112:115], v[8:11]
	v_mfma_f32_16x16x32_bf16 v[4:7], v[80:83], v[120:123], v[4:7]
	v_mfma_f32_16x16x32_bf16 v[0:3], v[88:91], v[120:123], v[0:3]
	s_setprio 0
	s_setprio 1
	s_setprio 0
	s_barrier
	s_add_i32 s1, s1, 2
	s_cmp_gt_u32 s1, 13
	s_mov_b64 s[50:51], s[46:47]
	s_cbranch_scc0 .LBB0_306
	s_andn2_b64 vcc, exec, s[38:39]
	s_cbranch_vccnz .LBB0_309
	v_mov_b32_e32 v0, 0
	s_mov_b32 s14, s86
	s_mov_b32 s22, s0
	s_mov_b64 s[24:25], s[36:37]
	s_mov_b64 s[28:29], s[34:35]
	s_mov_b32 s27, s43
	v_mov_b32_e32 v1, v0
	v_mov_b32_e32 v2, v0
	v_mov_b32_e32 v3, v0
	v_mov_b32_e32 v4, v0
	v_mov_b32_e32 v5, v0
	v_mov_b32_e32 v6, v0
	v_mov_b32_e32 v7, v0
	v_mov_b32_e32 v8, v0
	v_mov_b32_e32 v9, v0
	v_mov_b32_e32 v10, v0
	v_mov_b32_e32 v11, v0
	v_mov_b32_e32 v12, v0
	v_mov_b32_e32 v13, v0
	v_mov_b32_e32 v14, v0
	v_mov_b32_e32 v15, v0
	v_mov_b32_e32 v16, v0
	v_mov_b32_e32 v17, v0
	v_mov_b32_e32 v18, v0
	v_mov_b32_e32 v19, v0
	v_mov_b32_e32 v20, v0
	v_mov_b32_e32 v21, v0
	v_mov_b32_e32 v22, v0
	v_mov_b32_e32 v23, v0
	v_mov_b32_e32 v24, v0
	v_mov_b32_e32 v25, v0
	v_mov_b32_e32 v26, v0
	v_mov_b32_e32 v27, v0
	v_mov_b32_e32 v28, v0
	v_mov_b32_e32 v29, v0
	v_mov_b32_e32 v30, v0
	v_mov_b32_e32 v31, v0
	v_mov_b32_e32 v32, v0
	v_mov_b32_e32 v33, v0
	v_mov_b32_e32 v34, v0
	v_mov_b32_e32 v35, v0
	v_mov_b32_e32 v36, v0
	v_mov_b32_e32 v37, v0
	v_mov_b32_e32 v38, v0
	v_mov_b32_e32 v39, v0
	v_mov_b32_e32 v40, v0
	v_mov_b32_e32 v41, v0
	v_mov_b32_e32 v42, v0
	v_mov_b32_e32 v43, v0
	v_mov_b32_e32 v44, v0
	v_mov_b32_e32 v45, v0
	v_mov_b32_e32 v46, v0
	v_mov_b32_e32 v47, v0
	v_mov_b32_e32 v48, v0
	v_mov_b32_e32 v49, v0
	v_mov_b32_e32 v50, v0
	v_mov_b32_e32 v51, v0
	v_mov_b32_e32 v52, v0
	v_mov_b32_e32 v53, v0
	v_mov_b32_e32 v54, v0
	v_mov_b32_e32 v55, v0
	v_mov_b32_e32 v56, v0
	v_mov_b32_e32 v57, v0
	v_mov_b32_e32 v58, v0
	v_mov_b32_e32 v59, v0
	v_mov_b32_e32 v60, v0
	v_mov_b32_e32 v61, v0
	v_mov_b32_e32 v62, v0
	v_mov_b32_e32 v63, v0

.LBB0_328:
	s_ashr_i32 s31, s30, 31
	s_lshl_b64 s[34:35], s[30:31], 19
	s_add_u32 s34, s84, s34
	s_addc_u32 s35, s85, s35
	s_and_b64 s[38:39], s[4:5], exec
	s_cselect_b32 s7, s35, s93
	s_cselect_b32 s11, s34, s92
	s_ashr_i32 s29, s28, 31
	s_lshl_b64 s[38:39], s[28:29], 19
	s_add_u32 s38, s56, s38
	s_addc_u32 s39, s57, s39
	s_and_b64 s[46:47], s[4:5], exec
	s_cselect_b32 s0, s39, s37
	s_cselect_b32 s29, s38, s36
	s_mov_b64 s[46:47], 0
	s_mov_b32 s31, -2
	v_add_u32_e32 v224, 0x10000, v184
	s_add_u32 s50, s46, 0x100
	s_addc_u32 s51, s47, 0
	s_add_u32 s3, s46, 0xfffff900
	s_addc_u32 s33, s47, -1
	s_cmp_gt_u32 s50, 0x7ff
	s_cselect_b32 s50, s3, s50
	s_cselect_b32 s51, s33, s51
	s_add_u32 s3, s92, s50
	s_addc_u32 s33, s93, s51
	s_add_u32 s43, s36, s50
	s_addc_u32 s54, s37, s51
	s_add_i32 s69, 0, 0x10000
	s_cmp_eq_u32 s31, 12
	s_cselect_b32 s97, s7, s33
	s_cselect_b32 s96, s11, s3
	s_cselect_b32 s95, s0, s54
	s_cselect_b32 s94, s29, s43
	s_add_i32 s3, 0, 0x14000
	ds_read_b128 v[40:43], v224
	ds_read_b128 v[60:63], v224 offset:1024
	ds_read_b128 v[80:83], v224 offset:2048
	ds_read_b128 v[100:103], v224 offset:3072
	ds_read_b128 v[120:123], v224 offset:16384
	ds_read_b128 v[140:143], v224 offset:17408
	ds_read_b128 v[152:155], v224 offset:18432
	ds_read_b128 v[168:171], v224 offset:19456
	s_add_u32 s33, s92, s46
	s_addc_u32 s43, s93, s47
	s_add_u32 s46, s33, 0x40080
	s_addc_u32 s47, s43, 0
	s_add_i32 m0, s23, 0xc000
	ds_read_b128 v[172:175], v202
	ds_read_b128 v[176:179], v202 offset:1024
	ds_read_b128 v[180:183], v202 offset:2048
	ds_read_b128 v[204:207], v202 offset:3072
	ds_read_b128 v[208:211], v202 offset:4096
	ds_read_b128 v[212:215], v202 offset:5120
	ds_read_b128 v[216:219], v202 offset:6144
	ds_read_b128 v[220:223], v202 offset:7168
	global_load_lds_dwordx4 v156, s[46:47]
	s_add_i32 m0, s23, 0xe000
	s_nop 0
	global_load_lds_dwordx4 v160, s[46:47]
	s_waitcnt vmcnt(8)
	s_waitcnt lgkmcnt(0)
	s_barrier
	s_setprio 1
	s_waitcnt lgkmcnt(0)
	v_mfma_f32_16x16x32_bf16 v[148:151], v[40:43], v[172:175], 0
	v_mfma_f32_16x16x32_bf16 v[144:147], v[80:83], v[172:175], 0
	v_mfma_f32_16x16x32_bf16 v[128:131], v[40:43], v[180:183], 0
	v_mfma_f32_16x16x32_bf16 v[124:127], v[80:83], v[180:183], 0
	v_mfma_f32_16x16x32_bf16 v[108:111], v[40:43], v[208:211], 0
	v_mfma_f32_16x16x32_bf16 v[104:107], v[80:83], v[208:211], 0
	v_mfma_f32_16x16x32_bf16 v[88:91], v[40:43], v[216:219], 0
	v_mfma_f32_16x16x32_bf16 v[84:87], v[80:83], v[216:219], 0
	v_mfma_f32_16x16x32_bf16 v[148:151], v[60:63], v[176:179], v[148:151]
	v_mfma_f32_16x16x32_bf16 v[144:147], v[100:103], v[176:179], v[144:147]
	v_mfma_f32_16x16x32_bf16 v[128:131], v[60:63], v[204:207], v[128:131]
	v_mfma_f32_16x16x32_bf16 v[124:127], v[100:103], v[204:207], v[124:127]
	v_mfma_f32_16x16x32_bf16 v[108:111], v[60:63], v[212:215], v[108:111]
	v_mfma_f32_16x16x32_bf16 v[104:107], v[100:103], v[212:215], v[104:107]
	v_mfma_f32_16x16x32_bf16 v[88:91], v[60:63], v[220:223], v[88:91]
	v_mfma_f32_16x16x32_bf16 v[84:87], v[100:103], v[220:223], v[84:87]
	s_setprio 0
	s_setprio 1
	v_mfma_f32_16x16x32_bf16 v[136:139], v[120:123], v[172:175], 0
	v_mfma_f32_16x16x32_bf16 v[132:135], v[152:155], v[172:175], 0
	v_mfma_f32_16x16x32_bf16 v[116:119], v[120:123], v[180:183], 0
	v_mfma_f32_16x16x32_bf16 v[112:115], v[152:155], v[180:183], 0
	v_mfma_f32_16x16x32_bf16 v[96:99], v[120:123], v[208:211], 0
	v_mfma_f32_16x16x32_bf16 v[92:95], v[152:155], v[208:211], 0
	v_mfma_f32_16x16x32_bf16 v[76:79], v[120:123], v[216:219], 0
	v_mfma_f32_16x16x32_bf16 v[72:75], v[152:155], v[216:219], 0
	v_mfma_f32_16x16x32_bf16 v[136:139], v[140:143], v[176:179], v[136:139]
	v_mfma_f32_16x16x32_bf16 v[132:135], v[168:171], v[176:179], v[132:135]
	v_mfma_f32_16x16x32_bf16 v[116:119], v[140:143], v[204:207], v[116:119]
	v_mfma_f32_16x16x32_bf16 v[112:115], v[168:171], v[204:207], v[112:115]
	v_mfma_f32_16x16x32_bf16 v[96:99], v[140:143], v[212:215], v[96:99]
	v_mfma_f32_16x16x32_bf16 v[92:95], v[168:171], v[212:215], v[92:95]
	v_mfma_f32_16x16x32_bf16 v[76:79], v[140:143], v[220:223], v[76:79]
	v_mfma_f32_16x16x32_bf16 v[72:75], v[168:171], v[220:223], v[72:75]
	s_setprio 0
	s_barrier
	s_add_i32 s33, s69, s60
	s_mov_b32 m0, s33
	ds_read_b128 v[172:175], v202 offset:16384
	ds_read_b128 v[176:179], v202 offset:17408
	ds_read_b128 v[180:183], v202 offset:18432
	ds_read_b128 v[204:207], v202 offset:19456
	ds_read_b128 v[208:211], v202 offset:20480
	ds_read_b128 v[212:215], v202 offset:21504
	ds_read_b128 v[216:219], v202 offset:22528
	ds_read_b128 v[220:223], v202 offset:23552
	global_load_lds_dwordx4 v158, s[94:95]
	s_add_i32 m0, s33, 0x2000
	s_add_u32 s46, s94, 0x40000
	s_addc_u32 s47, s95, 0
	s_add_i32 s3, s3, s60
	global_load_lds_dwordx4 v162, s[94:95]
	s_mov_b32 m0, s3
	s_nop 0
	global_load_lds_dwordx4 v158, s[46:47]
	s_add_i32 m0, s3, 0x2000
	s_nop 0
	global_load_lds_dwordx4 v162, s[46:47]
	s_mov_b32 m0, s23
	s_nop 0
	global_load_lds_dwordx4 v156, s[96:97]
	s_mov_b32 m0, s87
	s_nop 0
	global_load_lds_dwordx4 v160, s[96:97]
	s_waitcnt vmcnt(8)
	s_waitcnt lgkmcnt(0)
	s_barrier
	s_setprio 1
	s_waitcnt lgkmcnt(0)
	v_mfma_f32_16x16x32_bf16 v[68:71], v[40:43], v[172:175], 0
	v_mfma_f32_16x16x32_bf16 v[64:67], v[80:83], v[172:175], 0
	v_mfma_f32_16x16x32_bf16 v[48:51], v[40:43], v[180:183], 0
	v_mfma_f32_16x16x32_bf16 v[44:47], v[80:83], v[180:183], 0
	v_mfma_f32_16x16x32_bf16 v[28:31], v[40:43], v[208:211], 0
	v_mfma_f32_16x16x32_bf16 v[24:27], v[80:83], v[208:211], 0
	v_mfma_f32_16x16x32_bf16 v[12:15], v[40:43], v[216:219], 0
	v_mfma_f32_16x16x32_bf16 v[8:11], v[80:83], v[216:219], 0
	v_mfma_f32_16x16x32_bf16 v[68:71], v[60:63], v[176:179], v[68:71]
	v_mfma_f32_16x16x32_bf16 v[64:67], v[100:103], v[176:179], v[64:67]
	v_mfma_f32_16x16x32_bf16 v[48:51], v[60:63], v[204:207], v[48:51]
	v_mfma_f32_16x16x32_bf16 v[44:47], v[100:103], v[204:207], v[44:47]
	v_mfma_f32_16x16x32_bf16 v[28:31], v[60:63], v[212:215], v[28:31]
	v_mfma_f32_16x16x32_bf16 v[24:27], v[100:103], v[212:215], v[24:27]
	v_mfma_f32_16x16x32_bf16 v[12:15], v[60:63], v[220:223], v[12:15]
	v_mfma_f32_16x16x32_bf16 v[8:11], v[100:103], v[220:223], v[8:11]
	s_setprio 0
	s_setprio 1
	v_mfma_f32_16x16x32_bf16 v[52:55], v[152:155], v[172:175], 0
	v_mfma_f32_16x16x32_bf16 v[36:39], v[120:123], v[180:183], 0
	v_mfma_f32_16x16x32_bf16 v[32:35], v[152:155], v[180:183], 0
	v_mfma_f32_16x16x32_bf16 v[20:23], v[120:123], v[208:211], 0
	v_mfma_f32_16x16x32_bf16 v[16:19], v[152:155], v[208:211], 0
	v_mfma_f32_16x16x32_bf16 v[4:7], v[120:123], v[216:219], 0
	v_mfma_f32_16x16x32_bf16 v[0:3], v[152:155], v[216:219], 0
	v_mfma_f32_16x16x32_bf16 v[40:43], v[120:123], v[172:175], 0
	v_mfma_f32_16x16x32_bf16 v[52:55], v[168:171], v[176:179], v[52:55]
	v_mfma_f32_16x16x32_bf16 v[36:39], v[140:143], v[204:207], v[36:39]
	v_mfma_f32_16x16x32_bf16 v[32:35], v[168:171], v[204:207], v[32:35]
	v_mfma_f32_16x16x32_bf16 v[20:23], v[140:143], v[212:215], v[20:23]
	v_mfma_f32_16x16x32_bf16 v[16:19], v[168:171], v[212:215], v[16:19]
	v_mfma_f32_16x16x32_bf16 v[4:7], v[140:143], v[220:223], v[4:7]
	v_mfma_f32_16x16x32_bf16 v[0:3], v[168:171], v[220:223], v[0:3]
	v_mfma_f32_16x16x32_bf16 v[40:43], v[140:143], v[176:179], v[40:43]
	s_setprio 0
	s_barrier
	s_add_i32 s3, 0, 0x18000
	s_add_i32 s33, 0, 0x1c000
	ds_read_b128 v[56:59], v224 offset:32768
	ds_read_b128 v[60:63], v224 offset:33792
	ds_read_b128 v[80:83], v224 offset:34816
	ds_read_b128 v[100:103], v224 offset:35840
	ds_read_b128 v[120:123], v224 offset:49152
	ds_read_b128 v[140:143], v224 offset:50176
	ds_read_b128 v[152:155], v224 offset:51200
	ds_read_b128 v[168:171], v224 offset:52224
	s_add_u32 s46, s96, 0x40000
	s_addc_u32 s47, s97, 0
	s_mov_b32 m0, s89
	ds_read_b128 v[172:175], v202 offset:32768
	ds_read_b128 v[176:179], v202 offset:33792
	ds_read_b128 v[180:183], v202 offset:34816
	ds_read_b128 v[204:207], v202 offset:35840
	ds_read_b128 v[208:211], v202 offset:36864
	ds_read_b128 v[212:215], v202 offset:37888
	ds_read_b128 v[216:219], v202 offset:38912
	ds_read_b128 v[220:223], v202 offset:39936
	global_load_lds_dwordx4 v156, s[46:47]
	s_mov_b32 m0, s98
	s_nop 0
	global_load_lds_dwordx4 v160, s[46:47]
	s_waitcnt vmcnt(8)
	s_waitcnt lgkmcnt(0)
	s_barrier
	s_setprio 1
	s_waitcnt lgkmcnt(0)
	v_mfma_f32_16x16x32_bf16 v[148:151], v[56:59], v[172:175], v[148:151]
	v_mfma_f32_16x16x32_bf16 v[144:147], v[80:83], v[172:175], v[144:147]
	v_mfma_f32_16x16x32_bf16 v[128:131], v[56:59], v[180:183], v[128:131]
	v_mfma_f32_16x16x32_bf16 v[124:127], v[80:83], v[180:183], v[124:127]
	v_mfma_f32_16x16x32_bf16 v[108:111], v[56:59], v[208:211], v[108:111]
	v_mfma_f32_16x16x32_bf16 v[104:107], v[80:83], v[208:211], v[104:107]
	v_mfma_f32_16x16x32_bf16 v[88:91], v[56:59], v[216:219], v[88:91]
	v_mfma_f32_16x16x32_bf16 v[84:87], v[80:83], v[216:219], v[84:87]
	v_mfma_f32_16x16x32_bf16 v[148:151], v[60:63], v[176:179], v[148:151]
	v_mfma_f32_16x16x32_bf16 v[144:147], v[100:103], v[176:179], v[144:147]
	v_mfma_f32_16x16x32_bf16 v[128:131], v[60:63], v[204:207], v[128:131]
	v_mfma_f32_16x16x32_bf16 v[124:127], v[100:103], v[204:207], v[124:127]
	v_mfma_f32_16x16x32_bf16 v[108:111], v[60:63], v[212:215], v[108:111]
	v_mfma_f32_16x16x32_bf16 v[104:107], v[100:103], v[212:215], v[104:107]
	v_mfma_f32_16x16x32_bf16 v[88:91], v[60:63], v[220:223], v[88:91]
	v_mfma_f32_16x16x32_bf16 v[84:87], v[100:103], v[220:223], v[84:87]
	s_setprio 0
	s_setprio 1
	v_mfma_f32_16x16x32_bf16 v[136:139], v[120:123], v[172:175], v[136:139]
	v_mfma_f32_16x16x32_bf16 v[132:135], v[152:155], v[172:175], v[132:135]
	v_mfma_f32_16x16x32_bf16 v[116:119], v[120:123], v[180:183], v[116:119]
	v_mfma_f32_16x16x32_bf16 v[112:115], v[152:155], v[180:183], v[112:115]
	v_mfma_f32_16x16x32_bf16 v[96:99], v[120:123], v[208:211], v[96:99]
	v_mfma_f32_16x16x32_bf16 v[92:95], v[152:155], v[208:211], v[92:95]
	v_mfma_f32_16x16x32_bf16 v[76:79], v[120:123], v[216:219], v[76:79]
	v_mfma_f32_16x16x32_bf16 v[72:75], v[152:155], v[216:219], v[72:75]
	v_mfma_f32_16x16x32_bf16 v[136:139], v[140:143], v[176:179], v[136:139]
	v_mfma_f32_16x16x32_bf16 v[132:135], v[168:171], v[176:179], v[132:135]
	v_mfma_f32_16x16x32_bf16 v[116:119], v[140:143], v[204:207], v[116:119]
	v_mfma_f32_16x16x32_bf16 v[112:115], v[168:171], v[204:207], v[112:115]
	v_mfma_f32_16x16x32_bf16 v[96:99], v[140:143], v[212:215], v[96:99]
	v_mfma_f32_16x16x32_bf16 v[92:95], v[168:171], v[212:215], v[92:95]
	v_mfma_f32_16x16x32_bf16 v[76:79], v[140:143], v[220:223], v[76:79]
	v_mfma_f32_16x16x32_bf16 v[72:75], v[168:171], v[220:223], v[72:75]
	s_setprio 0
	s_barrier
	s_add_i32 s3, s3, s60
	s_add_u32 s100, s94, 0x80
	s_addc_u32 s101, s95, 0
	s_mov_b32 m0, s3
	ds_read_b128 v[172:175], v202 offset:49152
	ds_read_b128 v[176:179], v202 offset:50176
	ds_read_b128 v[180:183], v202 offset:51200
	ds_read_b128 v[204:207], v202 offset:52224
	ds_read_b128 v[208:211], v202 offset:53248
	ds_read_b128 v[212:215], v202 offset:54272
	ds_read_b128 v[216:219], v202 offset:55296
	ds_read_b128 v[220:223], v202 offset:56320
	global_load_lds_dwordx4 v158, s[100:101]
	s_add_i32 m0, s3, 0x2000
	s_add_u32 s46, s94, 0x40080
	s_addc_u32 s47, s95, 0
	s_add_i32 s3, s33, s60
	global_load_lds_dwordx4 v162, s[100:101]
	s_mov_b32 m0, s3
	s_nop 0
	global_load_lds_dwordx4 v158, s[46:47]
	s_add_i32 m0, s3, 0x2000
	s_nop 0
	global_load_lds_dwordx4 v162, s[46:47]
	s_add_u32 s100, s96, 0x80
	s_addc_u32 s101, s97, 0
	s_mov_b32 m0, s99
	s_nop 0
	global_load_lds_dwordx4 v156, s[100:101]
	s_mov_b32 m0, s16
	s_nop 0
	global_load_lds_dwordx4 v160, s[100:101]
	s_waitcnt vmcnt(8)
	s_waitcnt lgkmcnt(0)
	s_barrier
	s_setprio 1
	s_waitcnt lgkmcnt(0)
	v_mfma_f32_16x16x32_bf16 v[68:71], v[56:59], v[172:175], v[68:71]
	v_mfma_f32_16x16x32_bf16 v[64:67], v[80:83], v[172:175], v[64:67]
	v_mfma_f32_16x16x32_bf16 v[48:51], v[56:59], v[180:183], v[48:51]
	v_mfma_f32_16x16x32_bf16 v[44:47], v[80:83], v[180:183], v[44:47]
	v_mfma_f32_16x16x32_bf16 v[28:31], v[56:59], v[208:211], v[28:31]
	v_mfma_f32_16x16x32_bf16 v[24:27], v[80:83], v[208:211], v[24:27]
	v_mfma_f32_16x16x32_bf16 v[12:15], v[56:59], v[216:219], v[12:15]
	v_mfma_f32_16x16x32_bf16 v[8:11], v[80:83], v[216:219], v[8:11]
	v_mfma_f32_16x16x32_bf16 v[68:71], v[60:63], v[176:179], v[68:71]
	v_mfma_f32_16x16x32_bf16 v[64:67], v[100:103], v[176:179], v[64:67]
	v_mfma_f32_16x16x32_bf16 v[48:51], v[60:63], v[204:207], v[48:51]
	v_mfma_f32_16x16x32_bf16 v[44:47], v[100:103], v[204:207], v[44:47]
	v_mfma_f32_16x16x32_bf16 v[28:31], v[60:63], v[212:215], v[28:31]
	v_mfma_f32_16x16x32_bf16 v[24:27], v[100:103], v[212:215], v[24:27]
	v_mfma_f32_16x16x32_bf16 v[12:15], v[60:63], v[220:223], v[12:15]
	v_mfma_f32_16x16x32_bf16 v[8:11], v[100:103], v[220:223], v[8:11]
	s_setprio 0
	s_setprio 1
	v_mfma_f32_16x16x32_bf16 v[40:43], v[120:123], v[172:175], v[40:43]
	v_mfma_f32_16x16x32_bf16 v[56:59], v[140:143], v[176:179], v[40:43]
	v_mfma_f32_16x16x32_bf16 v[40:43], v[152:155], v[172:175], v[52:55]
	v_mfma_f32_16x16x32_bf16 v[36:39], v[120:123], v[180:183], v[36:39]
	v_mfma_f32_16x16x32_bf16 v[32:35], v[152:155], v[180:183], v[32:35]
	v_mfma_f32_16x16x32_bf16 v[20:23], v[120:123], v[208:211], v[20:23]
	v_mfma_f32_16x16x32_bf16 v[16:19], v[152:155], v[208:211], v[16:19]
	v_mfma_f32_16x16x32_bf16 v[4:7], v[120:123], v[216:219], v[4:7]
	v_mfma_f32_16x16x32_bf16 v[0:3], v[152:155], v[216:219], v[0:3]
	v_mfma_f32_16x16x32_bf16 v[52:55], v[168:171], v[176:179], v[40:43]
	v_mfma_f32_16x16x32_bf16 v[36:39], v[140:143], v[204:207], v[36:39]
	v_mfma_f32_16x16x32_bf16 v[32:35], v[168:171], v[204:207], v[32:35]
	v_mfma_f32_16x16x32_bf16 v[20:23], v[140:143], v[212:215], v[20:23]
	v_mfma_f32_16x16x32_bf16 v[16:19], v[168:171], v[212:215], v[16:19]
	v_mfma_f32_16x16x32_bf16 v[4:7], v[140:143], v[220:223], v[4:7]
	v_mfma_f32_16x16x32_bf16 v[0:3], v[168:171], v[220:223], v[0:3]
	s_setprio 0
	s_barrier
	s_add_i32 s31, s31, 2
	s_cmp_gt_u32 s31, 13
	s_mov_b64 s[46:47], s[50:51]
	s_cbranch_scc1 .Lpeel_exit_mixin
.LBB0_329:
	s_add_u32 s50, s46, 0x100
	s_addc_u32 s51, s47, 0
	s_add_u32 s3, s46, 0xfffff900
	s_addc_u32 s33, s47, -1
	s_cmp_gt_u32 s50, 0x7ff
	s_cselect_b32 s50, s3, s50
	s_cselect_b32 s51, s33, s51
	s_add_u32 s3, s92, s50
	s_addc_u32 s33, s93, s51
	s_add_u32 s43, s36, s50
	s_addc_u32 s54, s37, s51
	s_add_i32 s69, 0, 0x10000
	s_cmp_eq_u32 s31, 12
	s_cselect_b32 s97, s7, s33
	s_cselect_b32 s96, s11, s3
	s_cselect_b32 s95, s0, s54
	s_cselect_b32 s94, s29, s43
	s_add_i32 s3, 0, 0x14000
	ds_read_b128 v[40:43], v224
	ds_read_b128 v[60:63], v224 offset:1024
	ds_read_b128 v[80:83], v224 offset:2048
	ds_read_b128 v[100:103], v224 offset:3072
	ds_read_b128 v[120:123], v224 offset:16384
	ds_read_b128 v[140:143], v224 offset:17408
	ds_read_b128 v[152:155], v224 offset:18432
	ds_read_b128 v[168:171], v224 offset:19456
	s_add_u32 s33, s92, s46
	s_addc_u32 s43, s93, s47
	s_add_u32 s46, s33, 0x40080
	s_addc_u32 s47, s43, 0
	s_add_i32 m0, s23, 0xc000
	ds_read_b128 v[172:175], v202
	ds_read_b128 v[176:179], v202 offset:1024
	ds_read_b128 v[180:183], v202 offset:2048
	ds_read_b128 v[204:207], v202 offset:3072
	ds_read_b128 v[208:211], v202 offset:4096
	ds_read_b128 v[212:215], v202 offset:5120
	ds_read_b128 v[216:219], v202 offset:6144
	ds_read_b128 v[220:223], v202 offset:7168
	global_load_lds_dwordx4 v156, s[46:47]
	s_add_i32 m0, s23, 0xe000
	s_nop 0
	global_load_lds_dwordx4 v160, s[46:47]
	s_waitcnt vmcnt(8)
	s_waitcnt lgkmcnt(0)
	s_barrier
	s_setprio 1
	s_waitcnt lgkmcnt(0)
	v_mfma_f32_16x16x32_bf16 v[148:151], v[40:43], v[172:175], v[148:151]
	v_mfma_f32_16x16x32_bf16 v[144:147], v[80:83], v[172:175], v[144:147]
	v_mfma_f32_16x16x32_bf16 v[128:131], v[40:43], v[180:183], v[128:131]
	v_mfma_f32_16x16x32_bf16 v[124:127], v[80:83], v[180:183], v[124:127]
	v_mfma_f32_16x16x32_bf16 v[108:111], v[40:43], v[208:211], v[108:111]
	v_mfma_f32_16x16x32_bf16 v[104:107], v[80:83], v[208:211], v[104:107]
	v_mfma_f32_16x16x32_bf16 v[88:91], v[40:43], v[216:219], v[88:91]
	v_mfma_f32_16x16x32_bf16 v[84:87], v[80:83], v[216:219], v[84:87]
	v_mfma_f32_16x16x32_bf16 v[148:151], v[60:63], v[176:179], v[148:151]
	v_mfma_f32_16x16x32_bf16 v[144:147], v[100:103], v[176:179], v[144:147]
	v_mfma_f32_16x16x32_bf16 v[128:131], v[60:63], v[204:207], v[128:131]
	v_mfma_f32_16x16x32_bf16 v[124:127], v[100:103], v[204:207], v[124:127]
	v_mfma_f32_16x16x32_bf16 v[108:111], v[60:63], v[212:215], v[108:111]
	v_mfma_f32_16x16x32_bf16 v[104:107], v[100:103], v[212:215], v[104:107]
	v_mfma_f32_16x16x32_bf16 v[88:91], v[60:63], v[220:223], v[88:91]
	v_mfma_f32_16x16x32_bf16 v[84:87], v[100:103], v[220:223], v[84:87]
	s_setprio 0
	s_setprio 1
	v_mfma_f32_16x16x32_bf16 v[136:139], v[120:123], v[172:175], v[136:139]
	v_mfma_f32_16x16x32_bf16 v[132:135], v[152:155], v[172:175], v[132:135]
	v_mfma_f32_16x16x32_bf16 v[116:119], v[120:123], v[180:183], v[116:119]
	v_mfma_f32_16x16x32_bf16 v[112:115], v[152:155], v[180:183], v[112:115]
	v_mfma_f32_16x16x32_bf16 v[96:99], v[120:123], v[208:211], v[96:99]
	v_mfma_f32_16x16x32_bf16 v[92:95], v[152:155], v[208:211], v[92:95]
	v_mfma_f32_16x16x32_bf16 v[76:79], v[120:123], v[216:219], v[76:79]
	v_mfma_f32_16x16x32_bf16 v[72:75], v[152:155], v[216:219], v[72:75]
	v_mfma_f32_16x16x32_bf16 v[136:139], v[140:143], v[176:179], v[136:139]
	v_mfma_f32_16x16x32_bf16 v[132:135], v[168:171], v[176:179], v[132:135]
	v_mfma_f32_16x16x32_bf16 v[116:119], v[140:143], v[204:207], v[116:119]
	v_mfma_f32_16x16x32_bf16 v[112:115], v[168:171], v[204:207], v[112:115]
	v_mfma_f32_16x16x32_bf16 v[96:99], v[140:143], v[212:215], v[96:99]
	v_mfma_f32_16x16x32_bf16 v[92:95], v[168:171], v[212:215], v[92:95]
	v_mfma_f32_16x16x32_bf16 v[76:79], v[140:143], v[220:223], v[76:79]
	v_mfma_f32_16x16x32_bf16 v[72:75], v[168:171], v[220:223], v[72:75]
	s_setprio 0
	s_barrier
	s_add_i32 s33, s69, s60
	s_mov_b32 m0, s33
	ds_read_b128 v[172:175], v202 offset:16384
	ds_read_b128 v[176:179], v202 offset:17408
	ds_read_b128 v[180:183], v202 offset:18432
	ds_read_b128 v[204:207], v202 offset:19456
	ds_read_b128 v[208:211], v202 offset:20480
	ds_read_b128 v[212:215], v202 offset:21504
	ds_read_b128 v[216:219], v202 offset:22528
	ds_read_b128 v[220:223], v202 offset:23552
	global_load_lds_dwordx4 v158, s[94:95]
	s_add_i32 m0, s33, 0x2000
	s_add_u32 s46, s94, 0x40000
	s_addc_u32 s47, s95, 0
	s_add_i32 s3, s3, s60
	global_load_lds_dwordx4 v162, s[94:95]
	s_mov_b32 m0, s3
	s_nop 0
	global_load_lds_dwordx4 v158, s[46:47]
	s_add_i32 m0, s3, 0x2000
	s_nop 0
	global_load_lds_dwordx4 v162, s[46:47]
	s_mov_b32 m0, s23
	s_nop 0
	global_load_lds_dwordx4 v156, s[96:97]
	s_mov_b32 m0, s87
	s_nop 0
	global_load_lds_dwordx4 v160, s[96:97]
	s_waitcnt vmcnt(8)
	s_waitcnt lgkmcnt(0)
	s_barrier
	s_setprio 1
	s_waitcnt lgkmcnt(0)
	v_mfma_f32_16x16x32_bf16 v[68:71], v[40:43], v[172:175], v[68:71]
	v_mfma_f32_16x16x32_bf16 v[64:67], v[80:83], v[172:175], v[64:67]
	v_mfma_f32_16x16x32_bf16 v[48:51], v[40:43], v[180:183], v[48:51]
	v_mfma_f32_16x16x32_bf16 v[44:47], v[80:83], v[180:183], v[44:47]
	v_mfma_f32_16x16x32_bf16 v[28:31], v[40:43], v[208:211], v[28:31]
	v_mfma_f32_16x16x32_bf16 v[24:27], v[80:83], v[208:211], v[24:27]
	v_mfma_f32_16x16x32_bf16 v[12:15], v[40:43], v[216:219], v[12:15]
	v_mfma_f32_16x16x32_bf16 v[8:11], v[80:83], v[216:219], v[8:11]
	v_mfma_f32_16x16x32_bf16 v[68:71], v[60:63], v[176:179], v[68:71]
	v_mfma_f32_16x16x32_bf16 v[64:67], v[100:103], v[176:179], v[64:67]
	v_mfma_f32_16x16x32_bf16 v[48:51], v[60:63], v[204:207], v[48:51]
	v_mfma_f32_16x16x32_bf16 v[44:47], v[100:103], v[204:207], v[44:47]
	v_mfma_f32_16x16x32_bf16 v[28:31], v[60:63], v[212:215], v[28:31]
	v_mfma_f32_16x16x32_bf16 v[24:27], v[100:103], v[212:215], v[24:27]
	v_mfma_f32_16x16x32_bf16 v[12:15], v[60:63], v[220:223], v[12:15]
	v_mfma_f32_16x16x32_bf16 v[8:11], v[100:103], v[220:223], v[8:11]
	s_setprio 0
	s_setprio 1
	v_mfma_f32_16x16x32_bf16 v[52:55], v[152:155], v[172:175], v[52:55]
	v_mfma_f32_16x16x32_bf16 v[36:39], v[120:123], v[180:183], v[36:39]
	v_mfma_f32_16x16x32_bf16 v[32:35], v[152:155], v[180:183], v[32:35]
	v_mfma_f32_16x16x32_bf16 v[20:23], v[120:123], v[208:211], v[20:23]
	v_mfma_f32_16x16x32_bf16 v[16:19], v[152:155], v[208:211], v[16:19]
	v_mfma_f32_16x16x32_bf16 v[4:7], v[120:123], v[216:219], v[4:7]
	v_mfma_f32_16x16x32_bf16 v[0:3], v[152:155], v[216:219], v[0:3]
	v_mfma_f32_16x16x32_bf16 v[40:43], v[120:123], v[172:175], v[56:59]
	v_mfma_f32_16x16x32_bf16 v[52:55], v[168:171], v[176:179], v[52:55]
	v_mfma_f32_16x16x32_bf16 v[36:39], v[140:143], v[204:207], v[36:39]
	v_mfma_f32_16x16x32_bf16 v[32:35], v[168:171], v[204:207], v[32:35]
	v_mfma_f32_16x16x32_bf16 v[20:23], v[140:143], v[212:215], v[20:23]
	v_mfma_f32_16x16x32_bf16 v[16:19], v[168:171], v[212:215], v[16:19]
	v_mfma_f32_16x16x32_bf16 v[4:7], v[140:143], v[220:223], v[4:7]
	v_mfma_f32_16x16x32_bf16 v[0:3], v[168:171], v[220:223], v[0:3]
	v_mfma_f32_16x16x32_bf16 v[40:43], v[140:143], v[176:179], v[40:43]
	s_setprio 0
	s_barrier
	s_add_i32 s3, 0, 0x18000
	s_add_i32 s33, 0, 0x1c000
	ds_read_b128 v[56:59], v224 offset:32768
	ds_read_b128 v[60:63], v224 offset:33792
	ds_read_b128 v[80:83], v224 offset:34816
	ds_read_b128 v[100:103], v224 offset:35840
	ds_read_b128 v[120:123], v224 offset:49152
	ds_read_b128 v[140:143], v224 offset:50176
	ds_read_b128 v[152:155], v224 offset:51200
	ds_read_b128 v[168:171], v224 offset:52224
	s_add_u32 s46, s96, 0x40000
	s_addc_u32 s47, s97, 0
	s_mov_b32 m0, s89
	ds_read_b128 v[172:175], v202 offset:32768
	ds_read_b128 v[176:179], v202 offset:33792
	ds_read_b128 v[180:183], v202 offset:34816
	ds_read_b128 v[204:207], v202 offset:35840
	ds_read_b128 v[208:211], v202 offset:36864
	ds_read_b128 v[212:215], v202 offset:37888
	ds_read_b128 v[216:219], v202 offset:38912
	ds_read_b128 v[220:223], v202 offset:39936
	global_load_lds_dwordx4 v156, s[46:47]
	s_mov_b32 m0, s98
	s_nop 0
	global_load_lds_dwordx4 v160, s[46:47]
	s_waitcnt vmcnt(8)
	s_waitcnt lgkmcnt(0)
	s_barrier
	s_setprio 1
	s_waitcnt lgkmcnt(0)
	v_mfma_f32_16x16x32_bf16 v[148:151], v[56:59], v[172:175], v[148:151]
	v_mfma_f32_16x16x32_bf16 v[144:147], v[80:83], v[172:175], v[144:147]
	v_mfma_f32_16x16x32_bf16 v[128:131], v[56:59], v[180:183], v[128:131]
	v_mfma_f32_16x16x32_bf16 v[124:127], v[80:83], v[180:183], v[124:127]
	v_mfma_f32_16x16x32_bf16 v[108:111], v[56:59], v[208:211], v[108:111]
	v_mfma_f32_16x16x32_bf16 v[104:107], v[80:83], v[208:211], v[104:107]
	v_mfma_f32_16x16x32_bf16 v[88:91], v[56:59], v[216:219], v[88:91]
	v_mfma_f32_16x16x32_bf16 v[84:87], v[80:83], v[216:219], v[84:87]
	v_mfma_f32_16x16x32_bf16 v[148:151], v[60:63], v[176:179], v[148:151]
	v_mfma_f32_16x16x32_bf16 v[144:147], v[100:103], v[176:179], v[144:147]
	v_mfma_f32_16x16x32_bf16 v[128:131], v[60:63], v[204:207], v[128:131]
	v_mfma_f32_16x16x32_bf16 v[124:127], v[100:103], v[204:207], v[124:127]
	v_mfma_f32_16x16x32_bf16 v[108:111], v[60:63], v[212:215], v[108:111]
	v_mfma_f32_16x16x32_bf16 v[104:107], v[100:103], v[212:215], v[104:107]
	v_mfma_f32_16x16x32_bf16 v[88:91], v[60:63], v[220:223], v[88:91]
	v_mfma_f32_16x16x32_bf16 v[84:87], v[100:103], v[220:223], v[84:87]
	s_setprio 0
	s_setprio 1
	v_mfma_f32_16x16x32_bf16 v[136:139], v[120:123], v[172:175], v[136:139]
	v_mfma_f32_16x16x32_bf16 v[132:135], v[152:155], v[172:175], v[132:135]
	v_mfma_f32_16x16x32_bf16 v[116:119], v[120:123], v[180:183], v[116:119]
	v_mfma_f32_16x16x32_bf16 v[112:115], v[152:155], v[180:183], v[112:115]
	v_mfma_f32_16x16x32_bf16 v[96:99], v[120:123], v[208:211], v[96:99]
	v_mfma_f32_16x16x32_bf16 v[92:95], v[152:155], v[208:211], v[92:95]
	v_mfma_f32_16x16x32_bf16 v[76:79], v[120:123], v[216:219], v[76:79]
	v_mfma_f32_16x16x32_bf16 v[72:75], v[152:155], v[216:219], v[72:75]
	v_mfma_f32_16x16x32_bf16 v[136:139], v[140:143], v[176:179], v[136:139]
	v_mfma_f32_16x16x32_bf16 v[132:135], v[168:171], v[176:179], v[132:135]
	v_mfma_f32_16x16x32_bf16 v[116:119], v[140:143], v[204:207], v[116:119]
	v_mfma_f32_16x16x32_bf16 v[112:115], v[168:171], v[204:207], v[112:115]
	v_mfma_f32_16x16x32_bf16 v[96:99], v[140:143], v[212:215], v[96:99]
	v_mfma_f32_16x16x32_bf16 v[92:95], v[168:171], v[212:215], v[92:95]
	v_mfma_f32_16x16x32_bf16 v[76:79], v[140:143], v[220:223], v[76:79]
	v_mfma_f32_16x16x32_bf16 v[72:75], v[168:171], v[220:223], v[72:75]
	s_setprio 0
	s_barrier
	s_add_i32 s3, s3, s60
	s_add_u32 s100, s94, 0x80
	s_addc_u32 s101, s95, 0
	s_mov_b32 m0, s3
	ds_read_b128 v[172:175], v202 offset:49152
	ds_read_b128 v[176:179], v202 offset:50176
	ds_read_b128 v[180:183], v202 offset:51200
	ds_read_b128 v[204:207], v202 offset:52224
	ds_read_b128 v[208:211], v202 offset:53248
	ds_read_b128 v[212:215], v202 offset:54272
	ds_read_b128 v[216:219], v202 offset:55296
	ds_read_b128 v[220:223], v202 offset:56320
	global_load_lds_dwordx4 v158, s[100:101]
	s_add_i32 m0, s3, 0x2000
	s_add_u32 s46, s94, 0x40080
	s_addc_u32 s47, s95, 0
	s_add_i32 s3, s33, s60
	global_load_lds_dwordx4 v162, s[100:101]
	s_mov_b32 m0, s3
	s_nop 0
	global_load_lds_dwordx4 v158, s[46:47]
	s_add_i32 m0, s3, 0x2000
	s_nop 0
	global_load_lds_dwordx4 v162, s[46:47]
	s_add_u32 s100, s96, 0x80
	s_addc_u32 s101, s97, 0
	s_mov_b32 m0, s99
	s_nop 0
	global_load_lds_dwordx4 v156, s[100:101]
	s_mov_b32 m0, s16
	s_nop 0
	global_load_lds_dwordx4 v160, s[100:101]
	s_waitcnt vmcnt(8)
	s_waitcnt lgkmcnt(0)
	s_barrier
	s_setprio 1
	s_waitcnt lgkmcnt(0)
	v_mfma_f32_16x16x32_bf16 v[68:71], v[56:59], v[172:175], v[68:71]
	v_mfma_f32_16x16x32_bf16 v[64:67], v[80:83], v[172:175], v[64:67]
	v_mfma_f32_16x16x32_bf16 v[48:51], v[56:59], v[180:183], v[48:51]
	v_mfma_f32_16x16x32_bf16 v[44:47], v[80:83], v[180:183], v[44:47]
	v_mfma_f32_16x16x32_bf16 v[28:31], v[56:59], v[208:211], v[28:31]
	v_mfma_f32_16x16x32_bf16 v[24:27], v[80:83], v[208:211], v[24:27]
	v_mfma_f32_16x16x32_bf16 v[12:15], v[56:59], v[216:219], v[12:15]
	v_mfma_f32_16x16x32_bf16 v[8:11], v[80:83], v[216:219], v[8:11]
	v_mfma_f32_16x16x32_bf16 v[68:71], v[60:63], v[176:179], v[68:71]
	v_mfma_f32_16x16x32_bf16 v[64:67], v[100:103], v[176:179], v[64:67]
	v_mfma_f32_16x16x32_bf16 v[48:51], v[60:63], v[204:207], v[48:51]
	v_mfma_f32_16x16x32_bf16 v[44:47], v[100:103], v[204:207], v[44:47]
	v_mfma_f32_16x16x32_bf16 v[28:31], v[60:63], v[212:215], v[28:31]
	v_mfma_f32_16x16x32_bf16 v[24:27], v[100:103], v[212:215], v[24:27]
	v_mfma_f32_16x16x32_bf16 v[12:15], v[60:63], v[220:223], v[12:15]
	v_mfma_f32_16x16x32_bf16 v[8:11], v[100:103], v[220:223], v[8:11]
	s_setprio 0
	s_setprio 1
	v_mfma_f32_16x16x32_bf16 v[40:43], v[120:123], v[172:175], v[40:43]
	v_mfma_f32_16x16x32_bf16 v[56:59], v[140:143], v[176:179], v[40:43]
	v_mfma_f32_16x16x32_bf16 v[40:43], v[152:155], v[172:175], v[52:55]
	v_mfma_f32_16x16x32_bf16 v[36:39], v[120:123], v[180:183], v[36:39]
	v_mfma_f32_16x16x32_bf16 v[32:35], v[152:155], v[180:183], v[32:35]
	v_mfma_f32_16x16x32_bf16 v[20:23], v[120:123], v[208:211], v[20:23]
	v_mfma_f32_16x16x32_bf16 v[16:19], v[152:155], v[208:211], v[16:19]
	v_mfma_f32_16x16x32_bf16 v[4:7], v[120:123], v[216:219], v[4:7]
	v_mfma_f32_16x16x32_bf16 v[0:3], v[152:155], v[216:219], v[0:3]
	v_mfma_f32_16x16x32_bf16 v[52:55], v[168:171], v[176:179], v[40:43]
	v_mfma_f32_16x16x32_bf16 v[36:39], v[140:143], v[204:207], v[36:39]
	v_mfma_f32_16x16x32_bf16 v[32:35], v[168:171], v[204:207], v[32:35]
	v_mfma_f32_16x16x32_bf16 v[20:23], v[140:143], v[212:215], v[20:23]
	v_mfma_f32_16x16x32_bf16 v[16:19], v[168:171], v[212:215], v[16:19]
	v_mfma_f32_16x16x32_bf16 v[4:7], v[140:143], v[220:223], v[4:7]
	v_mfma_f32_16x16x32_bf16 v[0:3], v[168:171], v[220:223], v[0:3]
	s_setprio 0
	s_barrier
	s_add_i32 s31, s31, 2
	s_cmp_gt_u32 s31, 13
	s_mov_b64 s[46:47], s[50:51]
	s_cbranch_scc0 .LBB0_329

.LBB0_489:
	s_add_u32 s0, s34, s92
	s_addc_u32 s43, s35, 0
	s_mov_b64 s[36:37], 0
	s_mov_b32 s86, 0
	v_add_u32_e32 v212, 0x10000, v234
	s_add_u32 s38, s36, 0x100
	s_addc_u32 s39, s37, 0
	s_cmp_ge_u32 s38, s24
	s_cselect_b32 s47, s24, 0
	s_cselect_b32 s46, 0, 0
	s_sub_u32 s38, s38, s47
	s_subb_u32 s39, s39, s46
	s_sub_u32 s47, s36, s47
	s_subb_u32 s46, s37, s46
	s_add_u32 vcc_lo, s34, s47
	s_addc_u32 vcc_hi, s35, s46
	s_add_u32 vcc_lo, vcc_lo, 0x100
	s_addc_u32 vcc_hi, vcc_hi, 0
	s_add_u32 s47, s30, s47
	s_addc_u32 s46, s31, s46
	s_add_u32 s69, s47, 0x100
	s_addc_u32 s3, s46, 0
	s_add_i32 s33, 0, 0x10000
	s_cmp_eq_u32 s99, s86
	s_cselect_b32 s47, s11, vcc_hi
	s_cselect_b32 s46, s10, vcc_lo
	s_cselect_b32 vcc_hi, s29, s3
	s_cselect_b32 vcc_lo, s28, s69
	s_add_i32 s3, 0, 0x14000
	ds_read_b128 v[120:123], v212
	ds_read_b128 v[124:127], v212 offset:1024
	ds_read_b128 v[128:131], v212 offset:2048
	ds_read_b128 v[132:135], v212 offset:3072
	ds_read_b128 v[136:139], v212 offset:16384
	ds_read_b128 v[140:143], v212 offset:17408
	ds_read_b128 v[144:147], v212 offset:18432
	ds_read_b128 v[148:151], v212 offset:19456
	s_add_u32 s36, s0, s36
	s_addc_u32 s37, s43, s37
	s_add_u32 s100, s36, 0x80
	s_addc_u32 s101, s37, 0
	s_add_i32 m0, s94, 0xc000
	ds_read_b128 v[152:155], v248
	ds_read_b128 v[156:159], v248 offset:1024
	ds_read_b128 v[160:163], v248 offset:2048
	ds_read_b128 v[172:175], v248 offset:3072
	ds_read_b128 v[176:179], v248 offset:4096
	ds_read_b128 v[180:183], v248 offset:5120
	ds_read_b128 v[184:187], v248 offset:6144
	ds_read_b128 v[208:211], v248 offset:7168
	global_load_lds_dwordx4 v202, s[100:101]
	s_add_i32 m0, s94, 0xe000
	s_nop 0
	global_load_lds_dwordx4 v204, s[100:101]
	s_waitcnt vmcnt(8)
	s_waitcnt lgkmcnt(0)
	s_barrier
	s_setprio 1
	s_waitcnt lgkmcnt(0)
	v_mfma_f32_16x16x32_bf16 v[168:171], v[120:123], v[152:155], 0
	v_mfma_f32_16x16x32_bf16 v[164:167], v[128:131], v[152:155], 0
	v_mfma_f32_16x16x32_bf16 v[108:111], v[120:123], v[160:163], 0
	v_mfma_f32_16x16x32_bf16 v[104:107], v[128:131], v[160:163], 0
	v_mfma_f32_16x16x32_bf16 v[92:95], v[120:123], v[176:179], 0
	v_mfma_f32_16x16x32_bf16 v[88:91], v[128:131], v[176:179], 0
	v_mfma_f32_16x16x32_bf16 v[76:79], v[120:123], v[184:187], 0
	v_mfma_f32_16x16x32_bf16 v[72:75], v[128:131], v[184:187], 0
	v_mfma_f32_16x16x32_bf16 v[168:171], v[124:127], v[156:159], v[168:171]
	v_mfma_f32_16x16x32_bf16 v[164:167], v[132:135], v[156:159], v[164:167]
	v_mfma_f32_16x16x32_bf16 v[108:111], v[124:127], v[172:175], v[108:111]
	v_mfma_f32_16x16x32_bf16 v[104:107], v[132:135], v[172:175], v[104:107]
	v_mfma_f32_16x16x32_bf16 v[92:95], v[124:127], v[180:183], v[92:95]
	v_mfma_f32_16x16x32_bf16 v[88:91], v[132:135], v[180:183], v[88:91]
	v_mfma_f32_16x16x32_bf16 v[76:79], v[124:127], v[208:211], v[76:79]
	v_mfma_f32_16x16x32_bf16 v[72:75], v[132:135], v[208:211], v[72:75]
	s_setprio 0
	s_setprio 1
	v_mfma_f32_16x16x32_bf16 v[116:119], v[136:139], v[152:155], 0
	v_mfma_f32_16x16x32_bf16 v[112:115], v[144:147], v[152:155], 0
	v_mfma_f32_16x16x32_bf16 v[100:103], v[136:139], v[160:163], 0
	v_mfma_f32_16x16x32_bf16 v[96:99], v[144:147], v[160:163], 0
	v_mfma_f32_16x16x32_bf16 v[84:87], v[136:139], v[176:179], 0
	v_mfma_f32_16x16x32_bf16 v[80:83], v[144:147], v[176:179], 0
	v_mfma_f32_16x16x32_bf16 v[68:71], v[136:139], v[184:187], 0
	v_mfma_f32_16x16x32_bf16 v[64:67], v[144:147], v[184:187], 0
	v_mfma_f32_16x16x32_bf16 v[116:119], v[140:143], v[156:159], v[116:119]
	v_mfma_f32_16x16x32_bf16 v[112:115], v[148:151], v[156:159], v[112:115]
	v_mfma_f32_16x16x32_bf16 v[100:103], v[140:143], v[172:175], v[100:103]
	v_mfma_f32_16x16x32_bf16 v[96:99], v[148:151], v[172:175], v[96:99]
	v_mfma_f32_16x16x32_bf16 v[84:87], v[140:143], v[180:183], v[84:87]
	v_mfma_f32_16x16x32_bf16 v[80:83], v[148:151], v[180:183], v[80:83]
	v_mfma_f32_16x16x32_bf16 v[68:71], v[140:143], v[208:211], v[68:71]
	v_mfma_f32_16x16x32_bf16 v[64:67], v[148:151], v[208:211], v[64:67]
	s_setprio 0
	s_barrier
	s_add_i32 s33, s33, s89
	s_mov_b64 s[100:101], vcc
	s_mov_b32 m0, s33
	ds_read_b128 v[152:155], v248 offset:16384
	ds_read_b128 v[156:159], v248 offset:17408
	ds_read_b128 v[160:163], v248 offset:18432
	ds_read_b128 v[172:175], v248 offset:19456
	ds_read_b128 v[176:179], v248 offset:20480
	ds_read_b128 v[180:183], v248 offset:21504
	ds_read_b128 v[184:187], v248 offset:22528
	ds_read_b128 v[208:211], v248 offset:23552
	global_load_lds_dwordx4 v188, s[100:101]
	s_add_i32 m0, s33, 0x2000
	s_add_u32 s36, vcc_lo, s92
	s_addc_u32 s37, vcc_hi, 0
	s_add_i32 s3, s3, s89
	global_load_lds_dwordx4 v206, s[100:101]
	s_mov_b32 m0, s3
	s_nop 0
	global_load_lds_dwordx4 v188, s[36:37]
	s_add_i32 m0, s3, 0x2000
	s_nop 0
	global_load_lds_dwordx4 v206, s[36:37]
	s_mov_b32 m0, s94
	s_nop 0
	global_load_lds_dwordx4 v202, s[46:47]
	s_mov_b32 m0, s95
	s_nop 0
	global_load_lds_dwordx4 v204, s[46:47]
	s_waitcnt vmcnt(8)
	s_waitcnt lgkmcnt(0)
	s_barrier
	s_setprio 1
	s_waitcnt lgkmcnt(0)
	v_mfma_f32_16x16x32_bf16 v[60:63], v[120:123], v[152:155], 0
	v_mfma_f32_16x16x32_bf16 v[56:59], v[128:131], v[152:155], 0
	v_mfma_f32_16x16x32_bf16 v[44:47], v[120:123], v[160:163], 0
	v_mfma_f32_16x16x32_bf16 v[40:43], v[128:131], v[160:163], 0
	v_mfma_f32_16x16x32_bf16 v[28:31], v[120:123], v[176:179], 0
	v_mfma_f32_16x16x32_bf16 v[24:27], v[128:131], v[176:179], 0
	v_mfma_f32_16x16x32_bf16 v[12:15], v[120:123], v[184:187], 0
	v_mfma_f32_16x16x32_bf16 v[8:11], v[128:131], v[184:187], 0
	v_mfma_f32_16x16x32_bf16 v[60:63], v[124:127], v[156:159], v[60:63]
	v_mfma_f32_16x16x32_bf16 v[56:59], v[132:135], v[156:159], v[56:59]
	v_mfma_f32_16x16x32_bf16 v[44:47], v[124:127], v[172:175], v[44:47]
	v_mfma_f32_16x16x32_bf16 v[40:43], v[132:135], v[172:175], v[40:43]
	v_mfma_f32_16x16x32_bf16 v[28:31], v[124:127], v[180:183], v[28:31]
	v_mfma_f32_16x16x32_bf16 v[24:27], v[132:135], v[180:183], v[24:27]
	v_mfma_f32_16x16x32_bf16 v[12:15], v[124:127], v[208:211], v[12:15]
	v_mfma_f32_16x16x32_bf16 v[8:11], v[132:135], v[208:211], v[8:11]
	s_setprio 0
	s_setprio 1
	v_mfma_f32_16x16x32_bf16 v[52:55], v[136:139], v[152:155], 0
	v_mfma_f32_16x16x32_bf16 v[48:51], v[144:147], v[152:155], 0
	v_mfma_f32_16x16x32_bf16 v[36:39], v[136:139], v[160:163], 0
	v_mfma_f32_16x16x32_bf16 v[32:35], v[144:147], v[160:163], 0
	v_mfma_f32_16x16x32_bf16 v[20:23], v[136:139], v[176:179], 0
	v_mfma_f32_16x16x32_bf16 v[16:19], v[144:147], v[176:179], 0
	v_mfma_f32_16x16x32_bf16 v[4:7], v[136:139], v[184:187], 0
	v_mfma_f32_16x16x32_bf16 v[0:3], v[144:147], v[184:187], 0
	v_mfma_f32_16x16x32_bf16 v[52:55], v[140:143], v[156:159], v[52:55]
	v_mfma_f32_16x16x32_bf16 v[48:51], v[148:151], v[156:159], v[48:51]
	v_mfma_f32_16x16x32_bf16 v[36:39], v[140:143], v[172:175], v[36:39]
	v_mfma_f32_16x16x32_bf16 v[32:35], v[148:151], v[172:175], v[32:35]
	v_mfma_f32_16x16x32_bf16 v[20:23], v[140:143], v[180:183], v[20:23]
	v_mfma_f32_16x16x32_bf16 v[16:19], v[148:151], v[180:183], v[16:19]
	v_mfma_f32_16x16x32_bf16 v[4:7], v[140:143], v[208:211], v[4:7]
	v_mfma_f32_16x16x32_bf16 v[0:3], v[148:151], v[208:211], v[0:3]
	s_setprio 0
	s_barrier
	s_add_i32 s3, 0, 0x18000
	s_add_i32 s33, 0, 0x1c000
	ds_read_b128 v[120:123], v212 offset:32768
	ds_read_b128 v[124:127], v212 offset:33792
	ds_read_b128 v[128:131], v212 offset:34816
	ds_read_b128 v[132:135], v212 offset:35840
	ds_read_b128 v[136:139], v212 offset:49152
	ds_read_b128 v[140:143], v212 offset:50176
	ds_read_b128 v[144:147], v212 offset:51200
	ds_read_b128 v[148:151], v212 offset:52224
	s_add_u32 s36, s46, s92
	s_addc_u32 s37, s47, 0
	s_mov_b32 m0, s96
	ds_read_b128 v[152:155], v248 offset:32768
	ds_read_b128 v[156:159], v248 offset:33792
	ds_read_b128 v[160:163], v248 offset:34816
	ds_read_b128 v[172:175], v248 offset:35840
	ds_read_b128 v[176:179], v248 offset:36864
	ds_read_b128 v[180:183], v248 offset:37888
	ds_read_b128 v[184:187], v248 offset:38912
	ds_read_b128 v[208:211], v248 offset:39936
	global_load_lds_dwordx4 v202, s[36:37]
	s_mov_b32 m0, s97
	s_nop 0
	global_load_lds_dwordx4 v204, s[36:37]
	s_waitcnt vmcnt(8)
	s_waitcnt lgkmcnt(0)
	s_barrier
	s_setprio 1
	s_waitcnt lgkmcnt(0)
	v_mfma_f32_16x16x32_bf16 v[168:171], v[120:123], v[152:155], v[168:171]
	v_mfma_f32_16x16x32_bf16 v[164:167], v[128:131], v[152:155], v[164:167]
	v_mfma_f32_16x16x32_bf16 v[108:111], v[120:123], v[160:163], v[108:111]
	v_mfma_f32_16x16x32_bf16 v[104:107], v[128:131], v[160:163], v[104:107]
	v_mfma_f32_16x16x32_bf16 v[92:95], v[120:123], v[176:179], v[92:95]
	v_mfma_f32_16x16x32_bf16 v[88:91], v[128:131], v[176:179], v[88:91]
	v_mfma_f32_16x16x32_bf16 v[76:79], v[120:123], v[184:187], v[76:79]
	v_mfma_f32_16x16x32_bf16 v[72:75], v[128:131], v[184:187], v[72:75]
	v_mfma_f32_16x16x32_bf16 v[168:171], v[124:127], v[156:159], v[168:171]
	v_mfma_f32_16x16x32_bf16 v[164:167], v[132:135], v[156:159], v[164:167]
	v_mfma_f32_16x16x32_bf16 v[108:111], v[124:127], v[172:175], v[108:111]
	v_mfma_f32_16x16x32_bf16 v[104:107], v[132:135], v[172:175], v[104:107]
	v_mfma_f32_16x16x32_bf16 v[92:95], v[124:127], v[180:183], v[92:95]
	v_mfma_f32_16x16x32_bf16 v[88:91], v[132:135], v[180:183], v[88:91]
	v_mfma_f32_16x16x32_bf16 v[76:79], v[124:127], v[208:211], v[76:79]
	v_mfma_f32_16x16x32_bf16 v[72:75], v[132:135], v[208:211], v[72:75]
	s_setprio 0
	s_setprio 1
	v_mfma_f32_16x16x32_bf16 v[116:119], v[136:139], v[152:155], v[116:119]
	v_mfma_f32_16x16x32_bf16 v[112:115], v[144:147], v[152:155], v[112:115]
	v_mfma_f32_16x16x32_bf16 v[100:103], v[136:139], v[160:163], v[100:103]
	v_mfma_f32_16x16x32_bf16 v[96:99], v[144:147], v[160:163], v[96:99]
	v_mfma_f32_16x16x32_bf16 v[84:87], v[136:139], v[176:179], v[84:87]
	v_mfma_f32_16x16x32_bf16 v[80:83], v[144:147], v[176:179], v[80:83]
	v_mfma_f32_16x16x32_bf16 v[68:71], v[136:139], v[184:187], v[68:71]
	v_mfma_f32_16x16x32_bf16 v[64:67], v[144:147], v[184:187], v[64:67]
	v_mfma_f32_16x16x32_bf16 v[116:119], v[140:143], v[156:159], v[116:119]
	v_mfma_f32_16x16x32_bf16 v[112:115], v[148:151], v[156:159], v[112:115]
	v_mfma_f32_16x16x32_bf16 v[100:103], v[140:143], v[172:175], v[100:103]
	v_mfma_f32_16x16x32_bf16 v[96:99], v[148:151], v[172:175], v[96:99]
	v_mfma_f32_16x16x32_bf16 v[84:87], v[140:143], v[180:183], v[84:87]
	v_mfma_f32_16x16x32_bf16 v[80:83], v[148:151], v[180:183], v[80:83]
	v_mfma_f32_16x16x32_bf16 v[68:71], v[140:143], v[208:211], v[68:71]
	v_mfma_f32_16x16x32_bf16 v[64:67], v[148:151], v[208:211], v[64:67]
	s_setprio 0
	s_barrier
	s_add_i32 s3, s3, s89
	s_add_u32 s100, vcc_lo, 0x80
	s_addc_u32 s101, vcc_hi, 0
	s_mov_b32 m0, s3
	ds_read_b128 v[152:155], v248 offset:49152
	ds_read_b128 v[156:159], v248 offset:50176
	ds_read_b128 v[160:163], v248 offset:51200
	ds_read_b128 v[172:175], v248 offset:52224
	ds_read_b128 v[176:179], v248 offset:53248
	ds_read_b128 v[180:183], v248 offset:54272
	ds_read_b128 v[184:187], v248 offset:55296
	ds_read_b128 v[208:211], v248 offset:56320
	global_load_lds_dwordx4 v188, s[100:101]
	s_add_i32 m0, s3, 0x2000
	s_add_i32 s3, s33, s89
	global_load_lds_dwordx4 v206, s[100:101]
	s_add_u32 s36, s100, s92
	s_addc_u32 s37, s101, 0
	s_mov_b32 m0, s3
	s_nop 0
	global_load_lds_dwordx4 v188, s[36:37]
	s_add_i32 m0, s3, 0x2000
	s_nop 0
	global_load_lds_dwordx4 v206, s[36:37]
	s_add_u32 s100, s46, 0x80
	s_addc_u32 s101, s47, 0
	s_mov_b32 m0, s76
	s_nop 0
	global_load_lds_dwordx4 v202, s[100:101]
	s_mov_b32 m0, s77
	s_nop 0
	global_load_lds_dwordx4 v204, s[100:101]
	s_waitcnt vmcnt(8)
	s_waitcnt lgkmcnt(0)
	s_barrier
	s_setprio 1
	s_waitcnt lgkmcnt(0)
	v_mfma_f32_16x16x32_bf16 v[60:63], v[120:123], v[152:155], v[60:63]
	v_mfma_f32_16x16x32_bf16 v[56:59], v[128:131], v[152:155], v[56:59]
	v_mfma_f32_16x16x32_bf16 v[44:47], v[120:123], v[160:163], v[44:47]
	v_mfma_f32_16x16x32_bf16 v[40:43], v[128:131], v[160:163], v[40:43]
	v_mfma_f32_16x16x32_bf16 v[28:31], v[120:123], v[176:179], v[28:31]
	v_mfma_f32_16x16x32_bf16 v[24:27], v[128:131], v[176:179], v[24:27]
	v_mfma_f32_16x16x32_bf16 v[12:15], v[120:123], v[184:187], v[12:15]
	v_mfma_f32_16x16x32_bf16 v[8:11], v[128:131], v[184:187], v[8:11]
	v_mfma_f32_16x16x32_bf16 v[60:63], v[124:127], v[156:159], v[60:63]
	v_mfma_f32_16x16x32_bf16 v[56:59], v[132:135], v[156:159], v[56:59]
	v_mfma_f32_16x16x32_bf16 v[44:47], v[124:127], v[172:175], v[44:47]
	v_mfma_f32_16x16x32_bf16 v[40:43], v[132:135], v[172:175], v[40:43]
	v_mfma_f32_16x16x32_bf16 v[28:31], v[124:127], v[180:183], v[28:31]
	v_mfma_f32_16x16x32_bf16 v[24:27], v[132:135], v[180:183], v[24:27]
	v_mfma_f32_16x16x32_bf16 v[12:15], v[124:127], v[208:211], v[12:15]
	v_mfma_f32_16x16x32_bf16 v[8:11], v[132:135], v[208:211], v[8:11]
	s_setprio 0
	s_setprio 1
	v_mfma_f32_16x16x32_bf16 v[52:55], v[136:139], v[152:155], v[52:55]
	v_mfma_f32_16x16x32_bf16 v[48:51], v[144:147], v[152:155], v[48:51]
	v_mfma_f32_16x16x32_bf16 v[36:39], v[136:139], v[160:163], v[36:39]
	v_mfma_f32_16x16x32_bf16 v[32:35], v[144:147], v[160:163], v[32:35]
	v_mfma_f32_16x16x32_bf16 v[20:23], v[136:139], v[176:179], v[20:23]
	v_mfma_f32_16x16x32_bf16 v[16:19], v[144:147], v[176:179], v[16:19]
	v_mfma_f32_16x16x32_bf16 v[4:7], v[136:139], v[184:187], v[4:7]
	v_mfma_f32_16x16x32_bf16 v[0:3], v[144:147], v[184:187], v[0:3]
	v_mfma_f32_16x16x32_bf16 v[52:55], v[140:143], v[156:159], v[52:55]
	v_mfma_f32_16x16x32_bf16 v[48:51], v[148:151], v[156:159], v[48:51]
	v_mfma_f32_16x16x32_bf16 v[36:39], v[140:143], v[172:175], v[36:39]
	v_mfma_f32_16x16x32_bf16 v[32:35], v[148:151], v[172:175], v[32:35]
	v_mfma_f32_16x16x32_bf16 v[20:23], v[140:143], v[180:183], v[20:23]
	v_mfma_f32_16x16x32_bf16 v[16:19], v[148:151], v[180:183], v[16:19]
	v_mfma_f32_16x16x32_bf16 v[4:7], v[140:143], v[208:211], v[4:7]
	v_mfma_f32_16x16x32_bf16 v[0:3], v[148:151], v[208:211], v[0:3]
	s_setprio 0
	s_barrier
	s_add_i32 s86, s86, 2
	s_cmp_ge_u32 s86, s98
	s_mov_b64 s[36:37], s[38:39]
	s_cbranch_scc1 .Lpeel_exit_resid
.LBB0_490:
	s_add_u32 s38, s36, 0x100
	s_addc_u32 s39, s37, 0
	s_cmp_ge_u32 s38, s24
	s_cselect_b32 s47, s24, 0
	s_cselect_b32 s46, 0, 0
	s_sub_u32 s38, s38, s47
	s_subb_u32 s39, s39, s46
	s_sub_u32 s47, s36, s47
	s_subb_u32 s46, s37, s46
	s_add_u32 vcc_lo, s34, s47
	s_addc_u32 vcc_hi, s35, s46
	s_add_u32 vcc_lo, vcc_lo, 0x100
	s_addc_u32 vcc_hi, vcc_hi, 0
	s_add_u32 s47, s30, s47
	s_addc_u32 s46, s31, s46
	s_add_u32 s69, s47, 0x100
	s_addc_u32 s3, s46, 0
	s_add_i32 s33, 0, 0x10000
	s_cmp_eq_u32 s99, s86
	s_cselect_b32 s47, s11, vcc_hi
	s_cselect_b32 s46, s10, vcc_lo
	s_cselect_b32 vcc_hi, s29, s3
	s_cselect_b32 vcc_lo, s28, s69
	s_add_i32 s3, 0, 0x14000
	ds_read_b128 v[120:123], v212
	ds_read_b128 v[124:127], v212 offset:1024
	ds_read_b128 v[128:131], v212 offset:2048
	ds_read_b128 v[132:135], v212 offset:3072
	ds_read_b128 v[136:139], v212 offset:16384
	ds_read_b128 v[140:143], v212 offset:17408
	ds_read_b128 v[144:147], v212 offset:18432
	ds_read_b128 v[148:151], v212 offset:19456
	s_add_u32 s36, s0, s36
	s_addc_u32 s37, s43, s37
	s_add_u32 s100, s36, 0x80
	s_addc_u32 s101, s37, 0
	s_add_i32 m0, s94, 0xc000
	ds_read_b128 v[152:155], v248
	ds_read_b128 v[156:159], v248 offset:1024
	ds_read_b128 v[160:163], v248 offset:2048
	ds_read_b128 v[172:175], v248 offset:3072
	ds_read_b128 v[176:179], v248 offset:4096
	ds_read_b128 v[180:183], v248 offset:5120
	ds_read_b128 v[184:187], v248 offset:6144
	ds_read_b128 v[208:211], v248 offset:7168
	global_load_lds_dwordx4 v202, s[100:101]
	s_add_i32 m0, s94, 0xe000
	s_nop 0
	global_load_lds_dwordx4 v204, s[100:101]
	s_waitcnt vmcnt(8)
	s_waitcnt lgkmcnt(0)
	s_barrier
	s_setprio 1
	s_waitcnt lgkmcnt(0)
	v_mfma_f32_16x16x32_bf16 v[168:171], v[120:123], v[152:155], v[168:171]
	v_mfma_f32_16x16x32_bf16 v[164:167], v[128:131], v[152:155], v[164:167]
	v_mfma_f32_16x16x32_bf16 v[108:111], v[120:123], v[160:163], v[108:111]
	v_mfma_f32_16x16x32_bf16 v[104:107], v[128:131], v[160:163], v[104:107]
	v_mfma_f32_16x16x32_bf16 v[92:95], v[120:123], v[176:179], v[92:95]
	v_mfma_f32_16x16x32_bf16 v[88:91], v[128:131], v[176:179], v[88:91]
	v_mfma_f32_16x16x32_bf16 v[76:79], v[120:123], v[184:187], v[76:79]
	v_mfma_f32_16x16x32_bf16 v[72:75], v[128:131], v[184:187], v[72:75]
	v_mfma_f32_16x16x32_bf16 v[168:171], v[124:127], v[156:159], v[168:171]
	v_mfma_f32_16x16x32_bf16 v[164:167], v[132:135], v[156:159], v[164:167]
	v_mfma_f32_16x16x32_bf16 v[108:111], v[124:127], v[172:175], v[108:111]
	v_mfma_f32_16x16x32_bf16 v[104:107], v[132:135], v[172:175], v[104:107]
	v_mfma_f32_16x16x32_bf16 v[92:95], v[124:127], v[180:183], v[92:95]
	v_mfma_f32_16x16x32_bf16 v[88:91], v[132:135], v[180:183], v[88:91]
	v_mfma_f32_16x16x32_bf16 v[76:79], v[124:127], v[208:211], v[76:79]
	v_mfma_f32_16x16x32_bf16 v[72:75], v[132:135], v[208:211], v[72:75]
	s_setprio 0
	s_setprio 1
	v_mfma_f32_16x16x32_bf16 v[116:119], v[136:139], v[152:155], v[116:119]
	v_mfma_f32_16x16x32_bf16 v[112:115], v[144:147], v[152:155], v[112:115]
	v_mfma_f32_16x16x32_bf16 v[100:103], v[136:139], v[160:163], v[100:103]
	v_mfma_f32_16x16x32_bf16 v[96:99], v[144:147], v[160:163], v[96:99]
	v_mfma_f32_16x16x32_bf16 v[84:87], v[136:139], v[176:179], v[84:87]
	v_mfma_f32_16x16x32_bf16 v[80:83], v[144:147], v[176:179], v[80:83]
	v_mfma_f32_16x16x32_bf16 v[68:71], v[136:139], v[184:187], v[68:71]
	v_mfma_f32_16x16x32_bf16 v[64:67], v[144:147], v[184:187], v[64:67]
	v_mfma_f32_16x16x32_bf16 v[116:119], v[140:143], v[156:159], v[116:119]
	v_mfma_f32_16x16x32_bf16 v[112:115], v[148:151], v[156:159], v[112:115]
	v_mfma_f32_16x16x32_bf16 v[100:103], v[140:143], v[172:175], v[100:103]
	v_mfma_f32_16x16x32_bf16 v[96:99], v[148:151], v[172:175], v[96:99]
	v_mfma_f32_16x16x32_bf16 v[84:87], v[140:143], v[180:183], v[84:87]
	v_mfma_f32_16x16x32_bf16 v[80:83], v[148:151], v[180:183], v[80:83]
	v_mfma_f32_16x16x32_bf16 v[68:71], v[140:143], v[208:211], v[68:71]
	v_mfma_f32_16x16x32_bf16 v[64:67], v[148:151], v[208:211], v[64:67]
	s_setprio 0
	s_barrier
	s_add_i32 s33, s33, s89
	s_mov_b64 s[100:101], vcc
	s_mov_b32 m0, s33
	ds_read_b128 v[152:155], v248 offset:16384
	ds_read_b128 v[156:159], v248 offset:17408
	ds_read_b128 v[160:163], v248 offset:18432
	ds_read_b128 v[172:175], v248 offset:19456
	ds_read_b128 v[176:179], v248 offset:20480
	ds_read_b128 v[180:183], v248 offset:21504
	ds_read_b128 v[184:187], v248 offset:22528
	ds_read_b128 v[208:211], v248 offset:23552
	global_load_lds_dwordx4 v188, s[100:101]
	s_add_i32 m0, s33, 0x2000
	s_add_u32 s36, vcc_lo, s92
	s_addc_u32 s37, vcc_hi, 0
	s_add_i32 s3, s3, s89
	global_load_lds_dwordx4 v206, s[100:101]
	s_mov_b32 m0, s3
	s_nop 0
	global_load_lds_dwordx4 v188, s[36:37]
	s_add_i32 m0, s3, 0x2000
	s_nop 0
	global_load_lds_dwordx4 v206, s[36:37]
	s_mov_b32 m0, s94
	s_nop 0
	global_load_lds_dwordx4 v202, s[46:47]
	s_mov_b32 m0, s95
	s_nop 0
	global_load_lds_dwordx4 v204, s[46:47]
	s_waitcnt vmcnt(8)
	s_waitcnt lgkmcnt(0)
	s_barrier
	s_setprio 1
	s_waitcnt lgkmcnt(0)
	v_mfma_f32_16x16x32_bf16 v[60:63], v[120:123], v[152:155], v[60:63]
	v_mfma_f32_16x16x32_bf16 v[56:59], v[128:131], v[152:155], v[56:59]
	v_mfma_f32_16x16x32_bf16 v[44:47], v[120:123], v[160:163], v[44:47]
	v_mfma_f32_16x16x32_bf16 v[40:43], v[128:131], v[160:163], v[40:43]
	v_mfma_f32_16x16x32_bf16 v[28:31], v[120:123], v[176:179], v[28:31]
	v_mfma_f32_16x16x32_bf16 v[24:27], v[128:131], v[176:179], v[24:27]
	v_mfma_f32_16x16x32_bf16 v[12:15], v[120:123], v[184:187], v[12:15]
	v_mfma_f32_16x16x32_bf16 v[8:11], v[128:131], v[184:187], v[8:11]
	v_mfma_f32_16x16x32_bf16 v[60:63], v[124:127], v[156:159], v[60:63]
	v_mfma_f32_16x16x32_bf16 v[56:59], v[132:135], v[156:159], v[56:59]
	v_mfma_f32_16x16x32_bf16 v[44:47], v[124:127], v[172:175], v[44:47]
	v_mfma_f32_16x16x32_bf16 v[40:43], v[132:135], v[172:175], v[40:43]
	v_mfma_f32_16x16x32_bf16 v[28:31], v[124:127], v[180:183], v[28:31]
	v_mfma_f32_16x16x32_bf16 v[24:27], v[132:135], v[180:183], v[24:27]
	v_mfma_f32_16x16x32_bf16 v[12:15], v[124:127], v[208:211], v[12:15]
	v_mfma_f32_16x16x32_bf16 v[8:11], v[132:135], v[208:211], v[8:11]
	s_setprio 0
	s_setprio 1
	v_mfma_f32_16x16x32_bf16 v[52:55], v[136:139], v[152:155], v[52:55]
	v_mfma_f32_16x16x32_bf16 v[48:51], v[144:147], v[152:155], v[48:51]
	v_mfma_f32_16x16x32_bf16 v[36:39], v[136:139], v[160:163], v[36:39]
	v_mfma_f32_16x16x32_bf16 v[32:35], v[144:147], v[160:163], v[32:35]
	v_mfma_f32_16x16x32_bf16 v[20:23], v[136:139], v[176:179], v[20:23]
	v_mfma_f32_16x16x32_bf16 v[16:19], v[144:147], v[176:179], v[16:19]
	v_mfma_f32_16x16x32_bf16 v[4:7], v[136:139], v[184:187], v[4:7]
	v_mfma_f32_16x16x32_bf16 v[0:3], v[144:147], v[184:187], v[0:3]
	v_mfma_f32_16x16x32_bf16 v[52:55], v[140:143], v[156:159], v[52:55]
	v_mfma_f32_16x16x32_bf16 v[48:51], v[148:151], v[156:159], v[48:51]
	v_mfma_f32_16x16x32_bf16 v[36:39], v[140:143], v[172:175], v[36:39]
	v_mfma_f32_16x16x32_bf16 v[32:35], v[148:151], v[172:175], v[32:35]
	v_mfma_f32_16x16x32_bf16 v[20:23], v[140:143], v[180:183], v[20:23]
	v_mfma_f32_16x16x32_bf16 v[16:19], v[148:151], v[180:183], v[16:19]
	v_mfma_f32_16x16x32_bf16 v[4:7], v[140:143], v[208:211], v[4:7]
	v_mfma_f32_16x16x32_bf16 v[0:3], v[148:151], v[208:211], v[0:3]
	s_setprio 0
	s_barrier
	s_add_i32 s3, 0, 0x18000
	s_add_i32 s33, 0, 0x1c000
	ds_read_b128 v[120:123], v212 offset:32768
	ds_read_b128 v[124:127], v212 offset:33792
	ds_read_b128 v[128:131], v212 offset:34816
	ds_read_b128 v[132:135], v212 offset:35840
	ds_read_b128 v[136:139], v212 offset:49152
	ds_read_b128 v[140:143], v212 offset:50176
	ds_read_b128 v[144:147], v212 offset:51200
	ds_read_b128 v[148:151], v212 offset:52224
	s_add_u32 s36, s46, s92
	s_addc_u32 s37, s47, 0
	s_mov_b32 m0, s96
	ds_read_b128 v[152:155], v248 offset:32768
	ds_read_b128 v[156:159], v248 offset:33792
	ds_read_b128 v[160:163], v248 offset:34816
	ds_read_b128 v[172:175], v248 offset:35840
	ds_read_b128 v[176:179], v248 offset:36864
	ds_read_b128 v[180:183], v248 offset:37888
	ds_read_b128 v[184:187], v248 offset:38912
	ds_read_b128 v[208:211], v248 offset:39936
	global_load_lds_dwordx4 v202, s[36:37]
	s_mov_b32 m0, s97
	s_nop 0
	global_load_lds_dwordx4 v204, s[36:37]
	s_waitcnt vmcnt(8)
	s_waitcnt lgkmcnt(0)
	s_barrier
	s_setprio 1
	s_waitcnt lgkmcnt(0)
	v_mfma_f32_16x16x32_bf16 v[168:171], v[120:123], v[152:155], v[168:171]
	v_mfma_f32_16x16x32_bf16 v[164:167], v[128:131], v[152:155], v[164:167]
	v_mfma_f32_16x16x32_bf16 v[108:111], v[120:123], v[160:163], v[108:111]
	v_mfma_f32_16x16x32_bf16 v[104:107], v[128:131], v[160:163], v[104:107]
	v_mfma_f32_16x16x32_bf16 v[92:95], v[120:123], v[176:179], v[92:95]
	v_mfma_f32_16x16x32_bf16 v[88:91], v[128:131], v[176:179], v[88:91]
	v_mfma_f32_16x16x32_bf16 v[76:79], v[120:123], v[184:187], v[76:79]
	v_mfma_f32_16x16x32_bf16 v[72:75], v[128:131], v[184:187], v[72:75]
	v_mfma_f32_16x16x32_bf16 v[168:171], v[124:127], v[156:159], v[168:171]
	v_mfma_f32_16x16x32_bf16 v[164:167], v[132:135], v[156:159], v[164:167]
	v_mfma_f32_16x16x32_bf16 v[108:111], v[124:127], v[172:175], v[108:111]
	v_mfma_f32_16x16x32_bf16 v[104:107], v[132:135], v[172:175], v[104:107]
	v_mfma_f32_16x16x32_bf16 v[92:95], v[124:127], v[180:183], v[92:95]
	v_mfma_f32_16x16x32_bf16 v[88:91], v[132:135], v[180:183], v[88:91]
	v_mfma_f32_16x16x32_bf16 v[76:79], v[124:127], v[208:211], v[76:79]
	v_mfma_f32_16x16x32_bf16 v[72:75], v[132:135], v[208:211], v[72:75]
	s_setprio 0
	s_setprio 1
	v_mfma_f32_16x16x32_bf16 v[116:119], v[136:139], v[152:155], v[116:119]
	v_mfma_f32_16x16x32_bf16 v[112:115], v[144:147], v[152:155], v[112:115]
	v_mfma_f32_16x16x32_bf16 v[100:103], v[136:139], v[160:163], v[100:103]
	v_mfma_f32_16x16x32_bf16 v[96:99], v[144:147], v[160:163], v[96:99]
	v_mfma_f32_16x16x32_bf16 v[84:87], v[136:139], v[176:179], v[84:87]
	v_mfma_f32_16x16x32_bf16 v[80:83], v[144:147], v[176:179], v[80:83]
	v_mfma_f32_16x16x32_bf16 v[68:71], v[136:139], v[184:187], v[68:71]
	v_mfma_f32_16x16x32_bf16 v[64:67], v[144:147], v[184:187], v[64:67]
	v_mfma_f32_16x16x32_bf16 v[116:119], v[140:143], v[156:159], v[116:119]
	v_mfma_f32_16x16x32_bf16 v[112:115], v[148:151], v[156:159], v[112:115]
	v_mfma_f32_16x16x32_bf16 v[100:103], v[140:143], v[172:175], v[100:103]
	v_mfma_f32_16x16x32_bf16 v[96:99], v[148:151], v[172:175], v[96:99]
	v_mfma_f32_16x16x32_bf16 v[84:87], v[140:143], v[180:183], v[84:87]
	v_mfma_f32_16x16x32_bf16 v[80:83], v[148:151], v[180:183], v[80:83]
	v_mfma_f32_16x16x32_bf16 v[68:71], v[140:143], v[208:211], v[68:71]
	v_mfma_f32_16x16x32_bf16 v[64:67], v[148:151], v[208:211], v[64:67]
	s_setprio 0
	s_barrier
	s_add_i32 s3, s3, s89
	s_add_u32 s100, vcc_lo, 0x80
	s_addc_u32 s101, vcc_hi, 0
	s_mov_b32 m0, s3
	ds_read_b128 v[152:155], v248 offset:49152
	ds_read_b128 v[156:159], v248 offset:50176
	ds_read_b128 v[160:163], v248 offset:51200
	ds_read_b128 v[172:175], v248 offset:52224
	ds_read_b128 v[176:179], v248 offset:53248
	ds_read_b128 v[180:183], v248 offset:54272
	ds_read_b128 v[184:187], v248 offset:55296
	ds_read_b128 v[208:211], v248 offset:56320
	global_load_lds_dwordx4 v188, s[100:101]
	s_add_i32 m0, s3, 0x2000
	s_add_i32 s3, s33, s89
	global_load_lds_dwordx4 v206, s[100:101]
	s_add_u32 s36, s100, s92
	s_addc_u32 s37, s101, 0
	s_mov_b32 m0, s3
	s_nop 0
	global_load_lds_dwordx4 v188, s[36:37]
	s_add_i32 m0, s3, 0x2000
	s_nop 0
	global_load_lds_dwordx4 v206, s[36:37]
	s_add_u32 s100, s46, 0x80
	s_addc_u32 s101, s47, 0
	s_mov_b32 m0, s76
	s_nop 0
	global_load_lds_dwordx4 v202, s[100:101]
	s_mov_b32 m0, s77
	s_nop 0
	global_load_lds_dwordx4 v204, s[100:101]
	s_waitcnt vmcnt(8)
	s_waitcnt lgkmcnt(0)
	s_barrier
	s_setprio 1
	s_waitcnt lgkmcnt(0)
	v_mfma_f32_16x16x32_bf16 v[60:63], v[120:123], v[152:155], v[60:63]
	v_mfma_f32_16x16x32_bf16 v[56:59], v[128:131], v[152:155], v[56:59]
	v_mfma_f32_16x16x32_bf16 v[44:47], v[120:123], v[160:163], v[44:47]
	v_mfma_f32_16x16x32_bf16 v[40:43], v[128:131], v[160:163], v[40:43]
	v_mfma_f32_16x16x32_bf16 v[28:31], v[120:123], v[176:179], v[28:31]
	v_mfma_f32_16x16x32_bf16 v[24:27], v[128:131], v[176:179], v[24:27]
	v_mfma_f32_16x16x32_bf16 v[12:15], v[120:123], v[184:187], v[12:15]
	v_mfma_f32_16x16x32_bf16 v[8:11], v[128:131], v[184:187], v[8:11]
	v_mfma_f32_16x16x32_bf16 v[60:63], v[124:127], v[156:159], v[60:63]
	v_mfma_f32_16x16x32_bf16 v[56:59], v[132:135], v[156:159], v[56:59]
	v_mfma_f32_16x16x32_bf16 v[44:47], v[124:127], v[172:175], v[44:47]
	v_mfma_f32_16x16x32_bf16 v[40:43], v[132:135], v[172:175], v[40:43]
	v_mfma_f32_16x16x32_bf16 v[28:31], v[124:127], v[180:183], v[28:31]
	v_mfma_f32_16x16x32_bf16 v[24:27], v[132:135], v[180:183], v[24:27]
	v_mfma_f32_16x16x32_bf16 v[12:15], v[124:127], v[208:211], v[12:15]
	v_mfma_f32_16x16x32_bf16 v[8:11], v[132:135], v[208:211], v[8:11]
	s_setprio 0
	s_setprio 1
	v_mfma_f32_16x16x32_bf16 v[52:55], v[136:139], v[152:155], v[52:55]
	v_mfma_f32_16x16x32_bf16 v[48:51], v[144:147], v[152:155], v[48:51]
	v_mfma_f32_16x16x32_bf16 v[36:39], v[136:139], v[160:163], v[36:39]
	v_mfma_f32_16x16x32_bf16 v[32:35], v[144:147], v[160:163], v[32:35]
	v_mfma_f32_16x16x32_bf16 v[20:23], v[136:139], v[176:179], v[20:23]
	v_mfma_f32_16x16x32_bf16 v[16:19], v[144:147], v[176:179], v[16:19]
	v_mfma_f32_16x16x32_bf16 v[4:7], v[136:139], v[184:187], v[4:7]
	v_mfma_f32_16x16x32_bf16 v[0:3], v[144:147], v[184:187], v[0:3]
	v_mfma_f32_16x16x32_bf16 v[52:55], v[140:143], v[156:159], v[52:55]
	v_mfma_f32_16x16x32_bf16 v[48:51], v[148:151], v[156:159], v[48:51]
	v_mfma_f32_16x16x32_bf16 v[36:39], v[140:143], v[172:175], v[36:39]
	v_mfma_f32_16x16x32_bf16 v[32:35], v[148:151], v[172:175], v[32:35]
	v_mfma_f32_16x16x32_bf16 v[20:23], v[140:143], v[180:183], v[20:23]
	v_mfma_f32_16x16x32_bf16 v[16:19], v[148:151], v[180:183], v[16:19]
	v_mfma_f32_16x16x32_bf16 v[4:7], v[140:143], v[208:211], v[4:7]
	v_mfma_f32_16x16x32_bf16 v[0:3], v[148:151], v[208:211], v[0:3]
	s_setprio 0
	s_barrier
	s_add_i32 s86, s86, 2
	s_cmp_ge_u32 s86, s98
	s_mov_b64 s[36:37], s[38:39]
	s_cbranch_scc0 .LBB0_490

.LBB0_527:
	s_ashr_i32 s19, s18, 31
	s_lshl_b64 s[20:21], s[18:19], 19
	s_add_u32 s20, s50, s20
	s_addc_u32 s21, s51, s21
	s_and_b64 s[22:23], s[4:5], exec
	s_cselect_b32 s19, s21, s29
	s_cselect_b32 s25, s20, s28
	s_ashr_i32 s17, s16, 31
	s_lshl_b64 s[22:23], s[16:17], 19
	s_add_u32 s22, s46, s22
	s_addc_u32 s23, s47, s23
	s_and_b64 s[30:31], s[4:5], exec
	s_cselect_b32 s0, s23, s27
	s_cselect_b32 s17, s22, s26
	s_mov_b64 s[30:31], 0
	s_mov_b32 s43, -2
	v_add_u32_e32 v186, 0x10000, v141
	s_add_u32 s34, s30, 0x100
	s_addc_u32 s35, s31, 0
	s_add_u32 s38, s30, 0xfffff900
	s_addc_u32 s39, s31, -1
	s_cmp_gt_u32 s34, 0x7ff
	s_cselect_b32 s34, s38, s34
	s_cselect_b32 s35, s39, s35
	s_add_u32 s36, s28, s34
	s_addc_u32 s37, s29, s35
	s_add_u32 s76, s26, s34
	s_addc_u32 s77, s27, s35
	s_add_i32 s86, 0, 0x10000
	s_cmp_eq_u32 s43, 12
	s_cselect_b32 s39, s19, s37
	s_cselect_b32 s38, s25, s36
	s_cselect_b32 s37, s0, s77
	s_cselect_b32 s36, s17, s76
	s_add_i32 s76, 0, 0x14000
	ds_read_b128 v[96:99], v186
	ds_read_b128 v[150:153], v186 offset:1024
	ds_read_b128 v[154:157], v186 offset:2048
	ds_read_b128 v[158:161], v186 offset:3072
	ds_read_b128 v[162:165], v186 offset:16384
	ds_read_b128 v[166:169], v186 offset:17408
	ds_read_b128 v[170:173], v186 offset:18432
	ds_read_b128 v[174:177], v186 offset:19456
	s_add_u32 s30, s28, s30
	s_addc_u32 s31, s29, s31
	s_add_u32 s30, s30, 0x40080
	s_addc_u32 s31, s31, 0
	s_add_i32 m0, s60, 0xc000
	ds_read_b128 v[178:181], v149
	ds_read_b128 v[182:185], v149 offset:1024
	ds_read_b128 v[202:205], v149 offset:2048
	ds_read_b128 v[206:209], v149 offset:3072
	ds_read_b128 v[210:213], v149 offset:4096
	ds_read_b128 v[214:217], v149 offset:5120
	ds_read_b128 v[218:221], v149 offset:6144
	ds_read_b128 v[222:225], v149 offset:7168
	global_load_lds_dwordx4 v136, s[30:31]
	s_add_i32 m0, s60, 0xe000
	s_nop 0
	global_load_lds_dwordx4 v134, s[30:31]
	s_waitcnt vmcnt(8)
	s_waitcnt lgkmcnt(0)
	s_barrier
	s_setprio 1
	s_waitcnt lgkmcnt(0)
	v_mfma_f32_16x16x32_bf16 v[128:131], v[96:99], v[178:181], 0
	v_mfma_f32_16x16x32_bf16 v[120:123], v[154:157], v[178:181], 0
	v_mfma_f32_16x16x32_bf16 v[112:115], v[96:99], v[202:205], 0
	v_mfma_f32_16x16x32_bf16 v[104:107], v[154:157], v[202:205], 0
	v_mfma_f32_16x16x32_bf16 v[92:95], v[96:99], v[210:213], 0
	v_mfma_f32_16x16x32_bf16 v[84:87], v[154:157], v[210:213], 0
	v_mfma_f32_16x16x32_bf16 v[76:79], v[96:99], v[218:221], 0
	v_mfma_f32_16x16x32_bf16 v[68:71], v[154:157], v[218:221], 0
	v_mfma_f32_16x16x32_bf16 v[128:131], v[150:153], v[182:185], v[128:131]
	v_mfma_f32_16x16x32_bf16 v[120:123], v[158:161], v[182:185], v[120:123]
	v_mfma_f32_16x16x32_bf16 v[112:115], v[150:153], v[206:209], v[112:115]
	v_mfma_f32_16x16x32_bf16 v[104:107], v[158:161], v[206:209], v[104:107]
	v_mfma_f32_16x16x32_bf16 v[92:95], v[150:153], v[214:217], v[92:95]
	v_mfma_f32_16x16x32_bf16 v[84:87], v[158:161], v[214:217], v[84:87]
	v_mfma_f32_16x16x32_bf16 v[76:79], v[150:153], v[222:225], v[76:79]
	v_mfma_f32_16x16x32_bf16 v[68:71], v[158:161], v[222:225], v[68:71]
	s_setprio 0
	s_setprio 1
	v_mfma_f32_16x16x32_bf16 v[124:127], v[162:165], v[178:181], 0
	v_mfma_f32_16x16x32_bf16 v[116:119], v[170:173], v[178:181], 0
	v_mfma_f32_16x16x32_bf16 v[108:111], v[162:165], v[202:205], 0
	v_mfma_f32_16x16x32_bf16 v[100:103], v[170:173], v[202:205], 0
	v_mfma_f32_16x16x32_bf16 v[88:91], v[162:165], v[210:213], 0
	v_mfma_f32_16x16x32_bf16 v[80:83], v[170:173], v[210:213], 0
	v_mfma_f32_16x16x32_bf16 v[72:75], v[162:165], v[218:221], 0
	v_mfma_f32_16x16x32_bf16 v[64:67], v[170:173], v[218:221], 0
	v_mfma_f32_16x16x32_bf16 v[124:127], v[166:169], v[182:185], v[124:127]
	v_mfma_f32_16x16x32_bf16 v[116:119], v[174:177], v[182:185], v[116:119]
	v_mfma_f32_16x16x32_bf16 v[108:111], v[166:169], v[206:209], v[108:111]
	v_mfma_f32_16x16x32_bf16 v[100:103], v[174:177], v[206:209], v[100:103]
	v_mfma_f32_16x16x32_bf16 v[88:91], v[166:169], v[214:217], v[88:91]
	v_mfma_f32_16x16x32_bf16 v[80:83], v[174:177], v[214:217], v[80:83]
	v_mfma_f32_16x16x32_bf16 v[72:75], v[166:169], v[222:225], v[72:75]
	v_mfma_f32_16x16x32_bf16 v[64:67], v[174:177], v[222:225], v[64:67]
	s_setprio 0
	s_barrier
	s_add_i32 s30, s86, s56
	s_mov_b32 m0, s30
	ds_read_b128 v[178:181], v149 offset:16384
	ds_read_b128 v[182:185], v149 offset:17408
	ds_read_b128 v[202:205], v149 offset:18432
	ds_read_b128 v[206:209], v149 offset:19456
	ds_read_b128 v[210:213], v149 offset:20480
	ds_read_b128 v[214:217], v149 offset:21504
	ds_read_b128 v[218:221], v149 offset:22528
	ds_read_b128 v[222:225], v149 offset:23552
	global_load_lds_dwordx4 v188, s[36:37]
	s_add_i32 m0, s30, 0x2000
	s_add_u32 s30, s36, 0x40000
	s_addc_u32 s31, s37, 0
	s_add_i32 s76, s76, s56
	global_load_lds_dwordx4 v132, s[36:37]
	s_mov_b32 m0, s76
	s_nop 0
	global_load_lds_dwordx4 v188, s[30:31]
	s_add_i32 m0, s76, 0x2000
	s_nop 0
	global_load_lds_dwordx4 v132, s[30:31]
	s_mov_b32 m0, s60
	s_nop 0
	global_load_lds_dwordx4 v136, s[38:39]
	s_mov_b32 m0, s71
	s_nop 0
	global_load_lds_dwordx4 v134, s[38:39]
	s_waitcnt vmcnt(8)
	s_waitcnt lgkmcnt(0)
	s_barrier
	s_setprio 1
	s_waitcnt lgkmcnt(0)
	v_mfma_f32_16x16x32_bf16 v[60:63], v[96:99], v[178:181], 0
	v_mfma_f32_16x16x32_bf16 v[52:55], v[154:157], v[178:181], 0
	v_mfma_f32_16x16x32_bf16 v[44:47], v[96:99], v[202:205], 0
	v_mfma_f32_16x16x32_bf16 v[36:39], v[154:157], v[202:205], 0
	v_mfma_f32_16x16x32_bf16 v[28:31], v[96:99], v[210:213], 0
	v_mfma_f32_16x16x32_bf16 v[20:23], v[154:157], v[210:213], 0
	v_mfma_f32_16x16x32_bf16 v[12:15], v[96:99], v[218:221], 0
	v_mfma_f32_16x16x32_bf16 v[4:7], v[154:157], v[218:221], 0
	v_mfma_f32_16x16x32_bf16 v[60:63], v[150:153], v[182:185], v[60:63]
	v_mfma_f32_16x16x32_bf16 v[52:55], v[158:161], v[182:185], v[52:55]
	v_mfma_f32_16x16x32_bf16 v[44:47], v[150:153], v[206:209], v[44:47]
	v_mfma_f32_16x16x32_bf16 v[36:39], v[158:161], v[206:209], v[36:39]
	v_mfma_f32_16x16x32_bf16 v[28:31], v[150:153], v[214:217], v[28:31]
	v_mfma_f32_16x16x32_bf16 v[20:23], v[158:161], v[214:217], v[20:23]
	v_mfma_f32_16x16x32_bf16 v[12:15], v[150:153], v[222:225], v[12:15]
	v_mfma_f32_16x16x32_bf16 v[4:7], v[158:161], v[222:225], v[4:7]
	s_setprio 0
	s_setprio 1
	v_mfma_f32_16x16x32_bf16 v[56:59], v[162:165], v[178:181], 0
	v_mfma_f32_16x16x32_bf16 v[48:51], v[170:173], v[178:181], 0
	v_mfma_f32_16x16x32_bf16 v[40:43], v[162:165], v[202:205], 0
	v_mfma_f32_16x16x32_bf16 v[32:35], v[170:173], v[202:205], 0
	v_mfma_f32_16x16x32_bf16 v[24:27], v[162:165], v[210:213], 0
	v_mfma_f32_16x16x32_bf16 v[16:19], v[170:173], v[210:213], 0
	v_mfma_f32_16x16x32_bf16 v[8:11], v[162:165], v[218:221], 0
	v_mfma_f32_16x16x32_bf16 v[0:3], v[170:173], v[218:221], 0
	v_mfma_f32_16x16x32_bf16 v[56:59], v[166:169], v[182:185], v[56:59]
	v_mfma_f32_16x16x32_bf16 v[48:51], v[174:177], v[182:185], v[48:51]
	v_mfma_f32_16x16x32_bf16 v[40:43], v[166:169], v[206:209], v[40:43]
	v_mfma_f32_16x16x32_bf16 v[32:35], v[174:177], v[206:209], v[32:35]
	v_mfma_f32_16x16x32_bf16 v[24:27], v[166:169], v[214:217], v[24:27]
	v_mfma_f32_16x16x32_bf16 v[16:19], v[174:177], v[214:217], v[16:19]
	v_mfma_f32_16x16x32_bf16 v[8:11], v[166:169], v[222:225], v[8:11]
	v_mfma_f32_16x16x32_bf16 v[0:3], v[174:177], v[222:225], v[0:3]
	s_setprio 0
	s_barrier
	s_add_i32 s76, 0, 0x18000
	s_add_i32 s77, 0, 0x1c000
	ds_read_b128 v[96:99], v186 offset:32768
	ds_read_b128 v[150:153], v186 offset:33792
	ds_read_b128 v[154:157], v186 offset:34816
	ds_read_b128 v[158:161], v186 offset:35840
	ds_read_b128 v[162:165], v186 offset:49152
	ds_read_b128 v[166:169], v186 offset:50176
	ds_read_b128 v[170:173], v186 offset:51200
	ds_read_b128 v[174:177], v186 offset:52224
	s_add_u32 s30, s38, 0x40000
	s_addc_u32 s31, s39, 0
	s_mov_b32 m0, s87
	ds_read_b128 v[178:181], v149 offset:32768
	ds_read_b128 v[182:185], v149 offset:33792
	ds_read_b128 v[202:205], v149 offset:34816
	ds_read_b128 v[206:209], v149 offset:35840
	ds_read_b128 v[210:213], v149 offset:36864
	ds_read_b128 v[214:217], v149 offset:37888
	ds_read_b128 v[218:221], v149 offset:38912
	ds_read_b128 v[222:225], v149 offset:39936
	global_load_lds_dwordx4 v136, s[30:31]
	s_mov_b32 m0, s89
	s_nop 0
	global_load_lds_dwordx4 v134, s[30:31]
	s_waitcnt vmcnt(8)
	s_waitcnt lgkmcnt(0)
	s_barrier
	s_setprio 1
	s_waitcnt lgkmcnt(0)
	v_mfma_f32_16x16x32_bf16 v[128:131], v[96:99], v[178:181], v[128:131]
	v_mfma_f32_16x16x32_bf16 v[120:123], v[154:157], v[178:181], v[120:123]
	v_mfma_f32_16x16x32_bf16 v[112:115], v[96:99], v[202:205], v[112:115]
	v_mfma_f32_16x16x32_bf16 v[104:107], v[154:157], v[202:205], v[104:107]
	v_mfma_f32_16x16x32_bf16 v[92:95], v[96:99], v[210:213], v[92:95]
	v_mfma_f32_16x16x32_bf16 v[84:87], v[154:157], v[210:213], v[84:87]
	v_mfma_f32_16x16x32_bf16 v[76:79], v[96:99], v[218:221], v[76:79]
	v_mfma_f32_16x16x32_bf16 v[68:71], v[154:157], v[218:221], v[68:71]
	v_mfma_f32_16x16x32_bf16 v[128:131], v[150:153], v[182:185], v[128:131]
	v_mfma_f32_16x16x32_bf16 v[120:123], v[158:161], v[182:185], v[120:123]
	v_mfma_f32_16x16x32_bf16 v[112:115], v[150:153], v[206:209], v[112:115]
	v_mfma_f32_16x16x32_bf16 v[104:107], v[158:161], v[206:209], v[104:107]
	v_mfma_f32_16x16x32_bf16 v[92:95], v[150:153], v[214:217], v[92:95]
	v_mfma_f32_16x16x32_bf16 v[84:87], v[158:161], v[214:217], v[84:87]
	v_mfma_f32_16x16x32_bf16 v[76:79], v[150:153], v[222:225], v[76:79]
	v_mfma_f32_16x16x32_bf16 v[68:71], v[158:161], v[222:225], v[68:71]
	s_setprio 0
	s_setprio 1
	v_mfma_f32_16x16x32_bf16 v[124:127], v[162:165], v[178:181], v[124:127]
	v_mfma_f32_16x16x32_bf16 v[116:119], v[170:173], v[178:181], v[116:119]
	v_mfma_f32_16x16x32_bf16 v[108:111], v[162:165], v[202:205], v[108:111]
	v_mfma_f32_16x16x32_bf16 v[100:103], v[170:173], v[202:205], v[100:103]
	v_mfma_f32_16x16x32_bf16 v[88:91], v[162:165], v[210:213], v[88:91]
	v_mfma_f32_16x16x32_bf16 v[80:83], v[170:173], v[210:213], v[80:83]
	v_mfma_f32_16x16x32_bf16 v[72:75], v[162:165], v[218:221], v[72:75]
	v_mfma_f32_16x16x32_bf16 v[64:67], v[170:173], v[218:221], v[64:67]
	v_mfma_f32_16x16x32_bf16 v[124:127], v[166:169], v[182:185], v[124:127]
	v_mfma_f32_16x16x32_bf16 v[116:119], v[174:177], v[182:185], v[116:119]
	v_mfma_f32_16x16x32_bf16 v[108:111], v[166:169], v[206:209], v[108:111]
	v_mfma_f32_16x16x32_bf16 v[100:103], v[174:177], v[206:209], v[100:103]
	v_mfma_f32_16x16x32_bf16 v[88:91], v[166:169], v[214:217], v[88:91]
	v_mfma_f32_16x16x32_bf16 v[80:83], v[174:177], v[214:217], v[80:83]
	v_mfma_f32_16x16x32_bf16 v[72:75], v[166:169], v[222:225], v[72:75]
	v_mfma_f32_16x16x32_bf16 v[64:67], v[174:177], v[222:225], v[64:67]
	s_setprio 0
	s_barrier
	s_add_i32 s30, s76, s56
	s_add_u32 s100, s36, 0x80
	s_addc_u32 s101, s37, 0
	s_mov_b32 m0, s30
	ds_read_b128 v[178:181], v149 offset:49152
	ds_read_b128 v[182:185], v149 offset:50176
	ds_read_b128 v[202:205], v149 offset:51200
	ds_read_b128 v[206:209], v149 offset:52224
	ds_read_b128 v[210:213], v149 offset:53248
	ds_read_b128 v[214:217], v149 offset:54272
	ds_read_b128 v[218:221], v149 offset:55296
	ds_read_b128 v[222:225], v149 offset:56320
	global_load_lds_dwordx4 v188, s[100:101]
	s_add_i32 m0, s30, 0x2000
	s_add_u32 s30, s36, 0x40080
	s_addc_u32 s31, s37, 0
	s_add_i32 s36, s77, s56
	global_load_lds_dwordx4 v132, s[100:101]
	s_mov_b32 m0, s36
	s_nop 0
	global_load_lds_dwordx4 v188, s[30:31]
	s_add_i32 m0, s36, 0x2000
	s_nop 0
	global_load_lds_dwordx4 v132, s[30:31]
	s_add_u32 s100, s38, 0x80
	s_addc_u32 s101, s39, 0
	s_mov_b32 m0, s90
	s_nop 0
	global_load_lds_dwordx4 v136, s[100:101]
	s_mov_b32 m0, s91
	s_nop 0
	global_load_lds_dwordx4 v134, s[100:101]
	s_waitcnt vmcnt(8)
	s_waitcnt lgkmcnt(0)
	s_barrier
	s_setprio 1
	s_waitcnt lgkmcnt(0)
	v_mfma_f32_16x16x32_bf16 v[60:63], v[96:99], v[178:181], v[60:63]
	v_mfma_f32_16x16x32_bf16 v[52:55], v[154:157], v[178:181], v[52:55]
	v_mfma_f32_16x16x32_bf16 v[44:47], v[96:99], v[202:205], v[44:47]
	v_mfma_f32_16x16x32_bf16 v[36:39], v[154:157], v[202:205], v[36:39]
	v_mfma_f32_16x16x32_bf16 v[28:31], v[96:99], v[210:213], v[28:31]
	v_mfma_f32_16x16x32_bf16 v[20:23], v[154:157], v[210:213], v[20:23]
	v_mfma_f32_16x16x32_bf16 v[12:15], v[96:99], v[218:221], v[12:15]
	v_mfma_f32_16x16x32_bf16 v[4:7], v[154:157], v[218:221], v[4:7]
	v_mfma_f32_16x16x32_bf16 v[60:63], v[150:153], v[182:185], v[60:63]
	v_mfma_f32_16x16x32_bf16 v[52:55], v[158:161], v[182:185], v[52:55]
	v_mfma_f32_16x16x32_bf16 v[44:47], v[150:153], v[206:209], v[44:47]
	v_mfma_f32_16x16x32_bf16 v[36:39], v[158:161], v[206:209], v[36:39]
	v_mfma_f32_16x16x32_bf16 v[28:31], v[150:153], v[214:217], v[28:31]
	v_mfma_f32_16x16x32_bf16 v[20:23], v[158:161], v[214:217], v[20:23]
	v_mfma_f32_16x16x32_bf16 v[12:15], v[150:153], v[222:225], v[12:15]
	v_mfma_f32_16x16x32_bf16 v[4:7], v[158:161], v[222:225], v[4:7]
	s_setprio 0
	s_setprio 1
	v_mfma_f32_16x16x32_bf16 v[56:59], v[162:165], v[178:181], v[56:59]
	v_mfma_f32_16x16x32_bf16 v[48:51], v[170:173], v[178:181], v[48:51]
	v_mfma_f32_16x16x32_bf16 v[40:43], v[162:165], v[202:205], v[40:43]
	v_mfma_f32_16x16x32_bf16 v[32:35], v[170:173], v[202:205], v[32:35]
	v_mfma_f32_16x16x32_bf16 v[24:27], v[162:165], v[210:213], v[24:27]
	v_mfma_f32_16x16x32_bf16 v[16:19], v[170:173], v[210:213], v[16:19]
	v_mfma_f32_16x16x32_bf16 v[8:11], v[162:165], v[218:221], v[8:11]
	v_mfma_f32_16x16x32_bf16 v[0:3], v[170:173], v[218:221], v[0:3]
	v_mfma_f32_16x16x32_bf16 v[56:59], v[166:169], v[182:185], v[56:59]
	v_mfma_f32_16x16x32_bf16 v[48:51], v[174:177], v[182:185], v[48:51]
	v_mfma_f32_16x16x32_bf16 v[40:43], v[166:169], v[206:209], v[40:43]
	v_mfma_f32_16x16x32_bf16 v[32:35], v[174:177], v[206:209], v[32:35]
	v_mfma_f32_16x16x32_bf16 v[24:27], v[166:169], v[214:217], v[24:27]
	v_mfma_f32_16x16x32_bf16 v[16:19], v[174:177], v[214:217], v[16:19]
	v_mfma_f32_16x16x32_bf16 v[8:11], v[166:169], v[222:225], v[8:11]
	v_mfma_f32_16x16x32_bf16 v[0:3], v[174:177], v[222:225], v[0:3]
	s_setprio 0
	s_barrier
	s_add_i32 s43, s43, 2
	s_cmp_gt_u32 s43, 13
	s_mov_b64 s[30:31], s[34:35]
	s_cbranch_scc1 .Lpeel_exit_swiglu
.LBB0_528:
	s_add_u32 s34, s30, 0x100
	s_addc_u32 s35, s31, 0
	s_add_u32 s38, s30, 0xfffff900
	s_addc_u32 s39, s31, -1
	s_cmp_gt_u32 s34, 0x7ff
	s_cselect_b32 s34, s38, s34
	s_cselect_b32 s35, s39, s35
	s_add_u32 s36, s28, s34
	s_addc_u32 s37, s29, s35
	s_add_u32 s76, s26, s34
	s_addc_u32 s77, s27, s35
	s_add_i32 s86, 0, 0x10000
	s_cmp_eq_u32 s43, 12
	s_cselect_b32 s39, s19, s37
	s_cselect_b32 s38, s25, s36
	s_cselect_b32 s37, s0, s77
	s_cselect_b32 s36, s17, s76
	s_add_i32 s76, 0, 0x14000
	ds_read_b128 v[96:99], v186
	ds_read_b128 v[150:153], v186 offset:1024
	ds_read_b128 v[154:157], v186 offset:2048
	ds_read_b128 v[158:161], v186 offset:3072
	ds_read_b128 v[162:165], v186 offset:16384
	ds_read_b128 v[166:169], v186 offset:17408
	ds_read_b128 v[170:173], v186 offset:18432
	ds_read_b128 v[174:177], v186 offset:19456
	s_add_u32 s30, s28, s30
	s_addc_u32 s31, s29, s31
	s_add_u32 s30, s30, 0x40080
	s_addc_u32 s31, s31, 0
	s_add_i32 m0, s60, 0xc000
	ds_read_b128 v[178:181], v149
	ds_read_b128 v[182:185], v149 offset:1024
	ds_read_b128 v[202:205], v149 offset:2048
	ds_read_b128 v[206:209], v149 offset:3072
	ds_read_b128 v[210:213], v149 offset:4096
	ds_read_b128 v[214:217], v149 offset:5120
	ds_read_b128 v[218:221], v149 offset:6144
	ds_read_b128 v[222:225], v149 offset:7168
	global_load_lds_dwordx4 v136, s[30:31]
	s_add_i32 m0, s60, 0xe000
	s_nop 0
	global_load_lds_dwordx4 v134, s[30:31]
	s_waitcnt vmcnt(8)
	s_waitcnt lgkmcnt(0)
	s_barrier
	s_setprio 1
	s_waitcnt lgkmcnt(0)
	v_mfma_f32_16x16x32_bf16 v[128:131], v[96:99], v[178:181], v[128:131]
	v_mfma_f32_16x16x32_bf16 v[120:123], v[154:157], v[178:181], v[120:123]
	v_mfma_f32_16x16x32_bf16 v[112:115], v[96:99], v[202:205], v[112:115]
	v_mfma_f32_16x16x32_bf16 v[104:107], v[154:157], v[202:205], v[104:107]
	v_mfma_f32_16x16x32_bf16 v[92:95], v[96:99], v[210:213], v[92:95]
	v_mfma_f32_16x16x32_bf16 v[84:87], v[154:157], v[210:213], v[84:87]
	v_mfma_f32_16x16x32_bf16 v[76:79], v[96:99], v[218:221], v[76:79]
	v_mfma_f32_16x16x32_bf16 v[68:71], v[154:157], v[218:221], v[68:71]
	v_mfma_f32_16x16x32_bf16 v[128:131], v[150:153], v[182:185], v[128:131]
	v_mfma_f32_16x16x32_bf16 v[120:123], v[158:161], v[182:185], v[120:123]
	v_mfma_f32_16x16x32_bf16 v[112:115], v[150:153], v[206:209], v[112:115]
	v_mfma_f32_16x16x32_bf16 v[104:107], v[158:161], v[206:209], v[104:107]
	v_mfma_f32_16x16x32_bf16 v[92:95], v[150:153], v[214:217], v[92:95]
	v_mfma_f32_16x16x32_bf16 v[84:87], v[158:161], v[214:217], v[84:87]
	v_mfma_f32_16x16x32_bf16 v[76:79], v[150:153], v[222:225], v[76:79]
	v_mfma_f32_16x16x32_bf16 v[68:71], v[158:161], v[222:225], v[68:71]
	s_setprio 0
	s_setprio 1
	v_mfma_f32_16x16x32_bf16 v[124:127], v[162:165], v[178:181], v[124:127]
	v_mfma_f32_16x16x32_bf16 v[116:119], v[170:173], v[178:181], v[116:119]
	v_mfma_f32_16x16x32_bf16 v[108:111], v[162:165], v[202:205], v[108:111]
	v_mfma_f32_16x16x32_bf16 v[100:103], v[170:173], v[202:205], v[100:103]
	v_mfma_f32_16x16x32_bf16 v[88:91], v[162:165], v[210:213], v[88:91]
	v_mfma_f32_16x16x32_bf16 v[80:83], v[170:173], v[210:213], v[80:83]
	v_mfma_f32_16x16x32_bf16 v[72:75], v[162:165], v[218:221], v[72:75]
	v_mfma_f32_16x16x32_bf16 v[64:67], v[170:173], v[218:221], v[64:67]
	v_mfma_f32_16x16x32_bf16 v[124:127], v[166:169], v[182:185], v[124:127]
	v_mfma_f32_16x16x32_bf16 v[116:119], v[174:177], v[182:185], v[116:119]
	v_mfma_f32_16x16x32_bf16 v[108:111], v[166:169], v[206:209], v[108:111]
	v_mfma_f32_16x16x32_bf16 v[100:103], v[174:177], v[206:209], v[100:103]
	v_mfma_f32_16x16x32_bf16 v[88:91], v[166:169], v[214:217], v[88:91]
	v_mfma_f32_16x16x32_bf16 v[80:83], v[174:177], v[214:217], v[80:83]
	v_mfma_f32_16x16x32_bf16 v[72:75], v[166:169], v[222:225], v[72:75]
	v_mfma_f32_16x16x32_bf16 v[64:67], v[174:177], v[222:225], v[64:67]
	s_setprio 0
	s_barrier
	s_add_i32 s30, s86, s56
	s_mov_b32 m0, s30
	ds_read_b128 v[178:181], v149 offset:16384
	ds_read_b128 v[182:185], v149 offset:17408
	ds_read_b128 v[202:205], v149 offset:18432
	ds_read_b128 v[206:209], v149 offset:19456
	ds_read_b128 v[210:213], v149 offset:20480
	ds_read_b128 v[214:217], v149 offset:21504
	ds_read_b128 v[218:221], v149 offset:22528
	ds_read_b128 v[222:225], v149 offset:23552
	global_load_lds_dwordx4 v188, s[36:37]
	s_add_i32 m0, s30, 0x2000
	s_add_u32 s30, s36, 0x40000
	s_addc_u32 s31, s37, 0
	s_add_i32 s76, s76, s56
	global_load_lds_dwordx4 v132, s[36:37]
	s_mov_b32 m0, s76
	s_nop 0
	global_load_lds_dwordx4 v188, s[30:31]
	s_add_i32 m0, s76, 0x2000
	s_nop 0
	global_load_lds_dwordx4 v132, s[30:31]
	s_mov_b32 m0, s60
	s_nop 0
	global_load_lds_dwordx4 v136, s[38:39]
	s_mov_b32 m0, s71
	s_nop 0
	global_load_lds_dwordx4 v134, s[38:39]
	s_waitcnt vmcnt(8)
	s_waitcnt lgkmcnt(0)
	s_barrier
	s_setprio 1
	s_waitcnt lgkmcnt(0)
	v_mfma_f32_16x16x32_bf16 v[60:63], v[96:99], v[178:181], v[60:63]
	v_mfma_f32_16x16x32_bf16 v[52:55], v[154:157], v[178:181], v[52:55]
	v_mfma_f32_16x16x32_bf16 v[44:47], v[96:99], v[202:205], v[44:47]
	v_mfma_f32_16x16x32_bf16 v[36:39], v[154:157], v[202:205], v[36:39]
	v_mfma_f32_16x16x32_bf16 v[28:31], v[96:99], v[210:213], v[28:31]
	v_mfma_f32_16x16x32_bf16 v[20:23], v[154:157], v[210:213], v[20:23]
	v_mfma_f32_16x16x32_bf16 v[12:15], v[96:99], v[218:221], v[12:15]
	v_mfma_f32_16x16x32_bf16 v[4:7], v[154:157], v[218:221], v[4:7]
	v_mfma_f32_16x16x32_bf16 v[60:63], v[150:153], v[182:185], v[60:63]
	v_mfma_f32_16x16x32_bf16 v[52:55], v[158:161], v[182:185], v[52:55]
	v_mfma_f32_16x16x32_bf16 v[44:47], v[150:153], v[206:209], v[44:47]
	v_mfma_f32_16x16x32_bf16 v[36:39], v[158:161], v[206:209], v[36:39]
	v_mfma_f32_16x16x32_bf16 v[28:31], v[150:153], v[214:217], v[28:31]
	v_mfma_f32_16x16x32_bf16 v[20:23], v[158:161], v[214:217], v[20:23]
	v_mfma_f32_16x16x32_bf16 v[12:15], v[150:153], v[222:225], v[12:15]
	v_mfma_f32_16x16x32_bf16 v[4:7], v[158:161], v[222:225], v[4:7]
	s_setprio 0
	s_setprio 1
	v_mfma_f32_16x16x32_bf16 v[56:59], v[162:165], v[178:181], v[56:59]
	v_mfma_f32_16x16x32_bf16 v[48:51], v[170:173], v[178:181], v[48:51]
	v_mfma_f32_16x16x32_bf16 v[40:43], v[162:165], v[202:205], v[40:43]
	v_mfma_f32_16x16x32_bf16 v[32:35], v[170:173], v[202:205], v[32:35]
	v_mfma_f32_16x16x32_bf16 v[24:27], v[162:165], v[210:213], v[24:27]
	v_mfma_f32_16x16x32_bf16 v[16:19], v[170:173], v[210:213], v[16:19]
	v_mfma_f32_16x16x32_bf16 v[8:11], v[162:165], v[218:221], v[8:11]
	v_mfma_f32_16x16x32_bf16 v[0:3], v[170:173], v[218:221], v[0:3]
	v_mfma_f32_16x16x32_bf16 v[56:59], v[166:169], v[182:185], v[56:59]
	v_mfma_f32_16x16x32_bf16 v[48:51], v[174:177], v[182:185], v[48:51]
	v_mfma_f32_16x16x32_bf16 v[40:43], v[166:169], v[206:209], v[40:43]
	v_mfma_f32_16x16x32_bf16 v[32:35], v[174:177], v[206:209], v[32:35]
	v_mfma_f32_16x16x32_bf16 v[24:27], v[166:169], v[214:217], v[24:27]
	v_mfma_f32_16x16x32_bf16 v[16:19], v[174:177], v[214:217], v[16:19]
	v_mfma_f32_16x16x32_bf16 v[8:11], v[166:169], v[222:225], v[8:11]
	v_mfma_f32_16x16x32_bf16 v[0:3], v[174:177], v[222:225], v[0:3]
	s_setprio 0
	s_barrier
	s_add_i32 s76, 0, 0x18000
	s_add_i32 s77, 0, 0x1c000
	ds_read_b128 v[96:99], v186 offset:32768
	ds_read_b128 v[150:153], v186 offset:33792
	ds_read_b128 v[154:157], v186 offset:34816
	ds_read_b128 v[158:161], v186 offset:35840
	ds_read_b128 v[162:165], v186 offset:49152
	ds_read_b128 v[166:169], v186 offset:50176
	ds_read_b128 v[170:173], v186 offset:51200
	ds_read_b128 v[174:177], v186 offset:52224
	s_add_u32 s30, s38, 0x40000
	s_addc_u32 s31, s39, 0
	s_mov_b32 m0, s87
	ds_read_b128 v[178:181], v149 offset:32768
	ds_read_b128 v[182:185], v149 offset:33792
	ds_read_b128 v[202:205], v149 offset:34816
	ds_read_b128 v[206:209], v149 offset:35840
	ds_read_b128 v[210:213], v149 offset:36864
	ds_read_b128 v[214:217], v149 offset:37888
	ds_read_b128 v[218:221], v149 offset:38912
	ds_read_b128 v[222:225], v149 offset:39936
	global_load_lds_dwordx4 v136, s[30:31]
	s_mov_b32 m0, s89
	s_nop 0
	global_load_lds_dwordx4 v134, s[30:31]
	s_waitcnt vmcnt(8)
	s_waitcnt lgkmcnt(0)
	s_barrier
	s_setprio 1
	s_waitcnt lgkmcnt(0)
	v_mfma_f32_16x16x32_bf16 v[128:131], v[96:99], v[178:181], v[128:131]
	v_mfma_f32_16x16x32_bf16 v[120:123], v[154:157], v[178:181], v[120:123]
	v_mfma_f32_16x16x32_bf16 v[112:115], v[96:99], v[202:205], v[112:115]
	v_mfma_f32_16x16x32_bf16 v[104:107], v[154:157], v[202:205], v[104:107]
	v_mfma_f32_16x16x32_bf16 v[92:95], v[96:99], v[210:213], v[92:95]
	v_mfma_f32_16x16x32_bf16 v[84:87], v[154:157], v[210:213], v[84:87]
	v_mfma_f32_16x16x32_bf16 v[76:79], v[96:99], v[218:221], v[76:79]
	v_mfma_f32_16x16x32_bf16 v[68:71], v[154:157], v[218:221], v[68:71]
	v_mfma_f32_16x16x32_bf16 v[128:131], v[150:153], v[182:185], v[128:131]
	v_mfma_f32_16x16x32_bf16 v[120:123], v[158:161], v[182:185], v[120:123]
	v_mfma_f32_16x16x32_bf16 v[112:115], v[150:153], v[206:209], v[112:115]
	v_mfma_f32_16x16x32_bf16 v[104:107], v[158:161], v[206:209], v[104:107]
	v_mfma_f32_16x16x32_bf16 v[92:95], v[150:153], v[214:217], v[92:95]
	v_mfma_f32_16x16x32_bf16 v[84:87], v[158:161], v[214:217], v[84:87]
	v_mfma_f32_16x16x32_bf16 v[76:79], v[150:153], v[222:225], v[76:79]
	v_mfma_f32_16x16x32_bf16 v[68:71], v[158:161], v[222:225], v[68:71]
	s_setprio 0
	s_setprio 1
	v_mfma_f32_16x16x32_bf16 v[124:127], v[162:165], v[178:181], v[124:127]
	v_mfma_f32_16x16x32_bf16 v[116:119], v[170:173], v[178:181], v[116:119]
	v_mfma_f32_16x16x32_bf16 v[108:111], v[162:165], v[202:205], v[108:111]
	v_mfma_f32_16x16x32_bf16 v[100:103], v[170:173], v[202:205], v[100:103]
	v_mfma_f32_16x16x32_bf16 v[88:91], v[162:165], v[210:213], v[88:91]
	v_mfma_f32_16x16x32_bf16 v[80:83], v[170:173], v[210:213], v[80:83]
	v_mfma_f32_16x16x32_bf16 v[72:75], v[162:165], v[218:221], v[72:75]
	v_mfma_f32_16x16x32_bf16 v[64:67], v[170:173], v[218:221], v[64:67]
	v_mfma_f32_16x16x32_bf16 v[124:127], v[166:169], v[182:185], v[124:127]
	v_mfma_f32_16x16x32_bf16 v[116:119], v[174:177], v[182:185], v[116:119]
	v_mfma_f32_16x16x32_bf16 v[108:111], v[166:169], v[206:209], v[108:111]
	v_mfma_f32_16x16x32_bf16 v[100:103], v[174:177], v[206:209], v[100:103]
	v_mfma_f32_16x16x32_bf16 v[88:91], v[166:169], v[214:217], v[88:91]
	v_mfma_f32_16x16x32_bf16 v[80:83], v[174:177], v[214:217], v[80:83]
	v_mfma_f32_16x16x32_bf16 v[72:75], v[166:169], v[222:225], v[72:75]
	v_mfma_f32_16x16x32_bf16 v[64:67], v[174:177], v[222:225], v[64:67]
	s_setprio 0
	s_barrier
	s_add_i32 s30, s76, s56
	s_add_u32 s100, s36, 0x80
	s_addc_u32 s101, s37, 0
	s_mov_b32 m0, s30
	ds_read_b128 v[178:181], v149 offset:49152
	ds_read_b128 v[182:185], v149 offset:50176
	ds_read_b128 v[202:205], v149 offset:51200
	ds_read_b128 v[206:209], v149 offset:52224
	ds_read_b128 v[210:213], v149 offset:53248
	ds_read_b128 v[214:217], v149 offset:54272
	ds_read_b128 v[218:221], v149 offset:55296
	ds_read_b128 v[222:225], v149 offset:56320
	global_load_lds_dwordx4 v188, s[100:101]
	s_add_i32 m0, s30, 0x2000
	s_add_u32 s30, s36, 0x40080
	s_addc_u32 s31, s37, 0
	s_add_i32 s36, s77, s56
	global_load_lds_dwordx4 v132, s[100:101]
	s_mov_b32 m0, s36
	s_nop 0
	global_load_lds_dwordx4 v188, s[30:31]
	s_add_i32 m0, s36, 0x2000
	s_nop 0
	global_load_lds_dwordx4 v132, s[30:31]
	s_add_u32 s100, s38, 0x80
	s_addc_u32 s101, s39, 0
	s_mov_b32 m0, s90
	s_nop 0
	global_load_lds_dwordx4 v136, s[100:101]
	s_mov_b32 m0, s91
	s_nop 0
	global_load_lds_dwordx4 v134, s[100:101]
	s_waitcnt vmcnt(8)
	s_waitcnt lgkmcnt(0)
	s_barrier
	s_setprio 1
	s_waitcnt lgkmcnt(0)
	v_mfma_f32_16x16x32_bf16 v[60:63], v[96:99], v[178:181], v[60:63]
	v_mfma_f32_16x16x32_bf16 v[52:55], v[154:157], v[178:181], v[52:55]
	v_mfma_f32_16x16x32_bf16 v[44:47], v[96:99], v[202:205], v[44:47]
	v_mfma_f32_16x16x32_bf16 v[36:39], v[154:157], v[202:205], v[36:39]
	v_mfma_f32_16x16x32_bf16 v[28:31], v[96:99], v[210:213], v[28:31]
	v_mfma_f32_16x16x32_bf16 v[20:23], v[154:157], v[210:213], v[20:23]
	v_mfma_f32_16x16x32_bf16 v[12:15], v[96:99], v[218:221], v[12:15]
	v_mfma_f32_16x16x32_bf16 v[4:7], v[154:157], v[218:221], v[4:7]
	v_mfma_f32_16x16x32_bf16 v[60:63], v[150:153], v[182:185], v[60:63]
	v_mfma_f32_16x16x32_bf16 v[52:55], v[158:161], v[182:185], v[52:55]
	v_mfma_f32_16x16x32_bf16 v[44:47], v[150:153], v[206:209], v[44:47]
	v_mfma_f32_16x16x32_bf16 v[36:39], v[158:161], v[206:209], v[36:39]
	v_mfma_f32_16x16x32_bf16 v[28:31], v[150:153], v[214:217], v[28:31]
	v_mfma_f32_16x16x32_bf16 v[20:23], v[158:161], v[214:217], v[20:23]
	v_mfma_f32_16x16x32_bf16 v[12:15], v[150:153], v[222:225], v[12:15]
	v_mfma_f32_16x16x32_bf16 v[4:7], v[158:161], v[222:225], v[4:7]
	s_setprio 0
	s_setprio 1
	v_mfma_f32_16x16x32_bf16 v[56:59], v[162:165], v[178:181], v[56:59]
	v_mfma_f32_16x16x32_bf16 v[48:51], v[170:173], v[178:181], v[48:51]
	v_mfma_f32_16x16x32_bf16 v[40:43], v[162:165], v[202:205], v[40:43]
	v_mfma_f32_16x16x32_bf16 v[32:35], v[170:173], v[202:205], v[32:35]
	v_mfma_f32_16x16x32_bf16 v[24:27], v[162:165], v[210:213], v[24:27]
	v_mfma_f32_16x16x32_bf16 v[16:19], v[170:173], v[210:213], v[16:19]
	v_mfma_f32_16x16x32_bf16 v[8:11], v[162:165], v[218:221], v[8:11]
	v_mfma_f32_16x16x32_bf16 v[0:3], v[170:173], v[218:221], v[0:3]
	v_mfma_f32_16x16x32_bf16 v[56:59], v[166:169], v[182:185], v[56:59]
	v_mfma_f32_16x16x32_bf16 v[48:51], v[174:177], v[182:185], v[48:51]
	v_mfma_f32_16x16x32_bf16 v[40:43], v[166:169], v[206:209], v[40:43]
	v_mfma_f32_16x16x32_bf16 v[32:35], v[174:177], v[206:209], v[32:35]
	v_mfma_f32_16x16x32_bf16 v[24:27], v[166:169], v[214:217], v[24:27]
	v_mfma_f32_16x16x32_bf16 v[16:19], v[174:177], v[214:217], v[16:19]
	v_mfma_f32_16x16x32_bf16 v[8:11], v[166:169], v[222:225], v[8:11]
	v_mfma_f32_16x16x32_bf16 v[0:3], v[174:177], v[222:225], v[0:3]
	s_setprio 0
	s_barrier
	s_add_i32 s43, s43, 2
	s_cmp_gt_u32 s43, 13
	s_mov_b64 s[30:31], s[34:35]
	s_cbranch_scc0 .LBB0_528
